# s5_item TM rows: heavy waves precompute Z=ap*bb per direction, then 16 ho accumulate c*Z with pk_fma (f32), light waves unchanged
# speedup vs baseline: 1.0439x; 1.0082x over previous
.LBB0_1710:
	s_or_b64 exec, exec, s[2:3]
	s_lshl_b32 s2, s59, 4
	s_or_b32 s2, s2, s58
	s_and_b32 s60, s23, 15
	s_ashr_i32 s3, s2, 31
	s_lshl_b64 s[20:21], s[2:3], 8
	s_lshl_b32 s61, s60, 4
	s_mov_b64 s[0:1], 0
	s_or_b32 s20, s20, s61
	s_waitcnt lgkmcnt(0)
	s_barrier
	s_and_saveexec_b64 s[24:25], s[42:43]
	s_cbranch_execz .LBB0_1723
	s_add_u32 s2, s78, s0
	s_addc_u32 s3, s79, s1
	s_lshl_b64 s[0:1], s[20:21], 10
	s_add_u32 s0, s2, s0
	s_addc_u32 s1, s3, s1
	s_add_i32 s2, s60, 1
	s_sub_i32 s3, 33, s60
	v_mov_b32_e32 v7, s2
	v_mov_b32_e32 v9, s3
	v_cndmask_b32_e64 v7, v7, v9, s[46:47]
	s_and_b32 s26, s23, 0xffffff00
	s_lshl_b32 s27, s58, 4
	v_lshl_add_u32 v9, v7, 9, s34
	v_sub_co_u32_e32 v7, vcc, s60, v5
	s_or_b32 s56, s27, s26
	s_xor_b64 s[26:27], vcc, -1
	v_lshl_add_u32 v24, v7, 9, s34
	v_subrev_co_u32_e32 v7, vcc, s60, v5
	v_lshl_add_u32 v25, v7, 9, s34
	v_or_b32_e32 v12, s56, v4
	v_mov_b32_e32 v7, v169
	v_ashrrev_i32_e32 v13, 31, v12
	v_lshl_add_u64 v[10:11], s[0:1], 0, v[6:7]
	s_mov_b64 s[0:1], 0x5500000
	s_xor_b64 s[54:55], vcc, -1
	v_cmp_eq_u32_e32 vcc, s60, v5
	v_lshl_add_u64 v[10:11], v[10:11], 0, s[0:1]
	v_lshl_add_u64 v[12:13], v[12:13], 2, s[86:87]
	s_mov_b64 s[56:57], 0
	v_mov_b32_e32 v7, v1
	s_and_b64 s[0:1], exec, s[44:45]
	s_cbranch_scc1 .LBB0_1714
	global_load_dword v26, v[12:13], off
	v_mov_b32_e32 v132, 0
	v_mov_b32_e32 v133, 0
	v_mov_b32_e32 v134, 0
	v_mov_b32_e32 v135, 0
	v_mov_b32_e32 v136, 0
	v_mov_b32_e32 v137, 0
	v_mov_b32_e32 v138, 0
	v_mov_b32_e32 v139, 0
	v_mov_b32_e32 v140, 0
	v_mov_b32_e32 v141, 0
	v_mov_b32_e32 v142, 0
	v_mov_b32_e32 v143, 0
	v_mov_b32_e32 v144, 0
	v_mov_b32_e32 v145, 0
	v_mov_b32_e32 v146, 0
	v_mov_b32_e32 v147, 0
	v_mov_b32_e32 v148, 0
	v_mov_b32_e32 v149, 0
	v_mov_b32_e32 v150, 0
	v_mov_b32_e32 v151, 0
	v_mov_b32_e32 v152, 0
	v_mov_b32_e32 v153, 0
	v_mov_b32_e32 v154, 0
	v_mov_b32_e32 v155, 0
	v_mov_b32_e32 v156, 0
	v_mov_b32_e32 v157, 0
	v_mov_b32_e32 v158, 0
	v_mov_b32_e32 v159, 0
	v_mov_b32_e32 v160, 0
	v_mov_b32_e32 v161, 0
	v_mov_b32_e32 v162, 0
	v_mov_b32_e32 v163, 0
	v_add_u32_e32 v58, 0x2200, v25
	s_mov_b32 s2, 0
.Ltmz_it:
	s_lshr_b32 s3, s2, 1
	s_and_b32 s56, s2, 1
	s_cmp_eq_u32 s3, 0
	s_cselect_b64 s[62:63], -1, 0
	s_cselect_b64 s[0:1], s[26:27], s[54:55]
	s_lshl_b32 s57, s56, 8
	v_cndmask_b32_e64 v56, v58, v24, s[62:63]
	v_add_u32_e32 v56, s57, v56
	s_lshl_b32 s3, s3, 13
	s_add_i32 s57, s57, s3
	s_add_i32 s57, s57, 0x1a400
	v_mov_b32_e32 v60, s57
	s_lshl_b32 s57, s56, 12
	s_add_i32 s57, s57, s3
	v_add_u32_e32 v57, s57, v16
	v_add_u32_e32 v59, 0x800, v57
	s_and_saveexec_b64 s[62:63], s[0:1]
	s_cbranch_execz .Ltmz_skip
	ds_read_b128 v[164:167], v56 offset:0
	ds_read_b128 v[194:197], v56 offset:16
	ds_read_b128 v[198:201], v56 offset:32
	ds_read_b128 v[202:205], v56 offset:48
	ds_read_b128 v[206:209], v56 offset:64
	ds_read_b128 v[210:213], v56 offset:80
	ds_read_b128 v[214:217], v56 offset:96
	ds_read_b128 v[218:221], v56 offset:112
	ds_read2_b64 v[186:189], v57 offset0:0 offset1:16
	ds_read2_b64 v[174:177], v57 offset0:32 offset1:48
	ds_read2_b64 v[32:35], v57 offset0:64 offset1:80
	ds_read2_b64 v[36:39], v57 offset0:96 offset1:112
	ds_read2_b64 v[40:43], v57 offset0:128 offset1:144
	ds_read2_b64 v[44:47], v57 offset0:160 offset1:176
	ds_read2_b64 v[48:51], v57 offset0:192 offset1:208
	ds_read2_b64 v[52:55], v57 offset0:224 offset1:240
	s_waitcnt lgkmcnt(7)
	v_mul_f32_e32 v27, v165, v187
	v_mul_f32_e32 v29, v165, v186
	v_fma_f32 v68, v164, v186, -v27
	v_fma_f32 v69, v164, v187, v29
	v_mul_f32_e32 v30, v167, v189
	v_mul_f32_e32 v31, v167, v188
	v_fma_f32 v70, v166, v188, -v30
	v_fma_f32 v71, v166, v189, v31
	s_waitcnt lgkmcnt(6)
	v_mul_f32_e32 v27, v195, v175
	v_mul_f32_e32 v29, v195, v174
	v_fma_f32 v72, v194, v174, -v27
	v_fma_f32 v73, v194, v175, v29
	v_mul_f32_e32 v30, v197, v177
	v_mul_f32_e32 v31, v197, v176
	v_fma_f32 v74, v196, v176, -v30
	v_fma_f32 v75, v196, v177, v31
	s_waitcnt lgkmcnt(5)
	v_mul_f32_e32 v27, v199, v33
	v_mul_f32_e32 v29, v199, v32
	v_fma_f32 v76, v198, v32, -v27
	v_fma_f32 v77, v198, v33, v29
	v_mul_f32_e32 v30, v201, v35
	v_mul_f32_e32 v31, v201, v34
	v_fma_f32 v78, v200, v34, -v30
	v_fma_f32 v79, v200, v35, v31
	s_waitcnt lgkmcnt(4)
	v_mul_f32_e32 v27, v203, v37
	v_mul_f32_e32 v29, v203, v36
	v_fma_f32 v80, v202, v36, -v27
	v_fma_f32 v81, v202, v37, v29
	v_mul_f32_e32 v30, v205, v39
	v_mul_f32_e32 v31, v205, v38
	v_fma_f32 v82, v204, v38, -v30
	v_fma_f32 v83, v204, v39, v31
	s_waitcnt lgkmcnt(3)
	v_mul_f32_e32 v27, v207, v41
	v_mul_f32_e32 v29, v207, v40
	v_fma_f32 v84, v206, v40, -v27
	v_fma_f32 v85, v206, v41, v29
	v_mul_f32_e32 v30, v209, v43
	v_mul_f32_e32 v31, v209, v42
	v_fma_f32 v86, v208, v42, -v30
	v_fma_f32 v87, v208, v43, v31
	s_waitcnt lgkmcnt(2)
	v_mul_f32_e32 v27, v211, v45
	v_mul_f32_e32 v29, v211, v44
	v_fma_f32 v88, v210, v44, -v27
	v_fma_f32 v89, v210, v45, v29
	v_mul_f32_e32 v30, v213, v47
	v_mul_f32_e32 v31, v213, v46
	v_fma_f32 v90, v212, v46, -v30
	v_fma_f32 v91, v212, v47, v31
	s_waitcnt lgkmcnt(1)
	v_mul_f32_e32 v27, v215, v49
	v_mul_f32_e32 v29, v215, v48
	v_fma_f32 v92, v214, v48, -v27
	v_fma_f32 v93, v214, v49, v29
	v_mul_f32_e32 v30, v217, v51
	v_mul_f32_e32 v31, v217, v50
	v_fma_f32 v94, v216, v50, -v30
	v_fma_f32 v95, v216, v51, v31
	s_waitcnt lgkmcnt(0)
	v_mul_f32_e32 v27, v219, v53
	v_mul_f32_e32 v29, v219, v52
	v_fma_f32 v96, v218, v52, -v27
	v_fma_f32 v97, v218, v53, v29
	v_mul_f32_e32 v30, v221, v55
	v_mul_f32_e32 v31, v221, v54
	v_fma_f32 v98, v220, v54, -v30
	v_fma_f32 v99, v220, v55, v31
	ds_read_b128 v[164:167], v56 offset:128
	ds_read_b128 v[194:197], v56 offset:144
	ds_read_b128 v[198:201], v56 offset:160
	ds_read_b128 v[202:205], v56 offset:176
	ds_read_b128 v[206:209], v56 offset:192
	ds_read_b128 v[210:213], v56 offset:208
	ds_read_b128 v[214:217], v56 offset:224
	ds_read_b128 v[218:221], v56 offset:240
	ds_read2_b64 v[186:189], v59 offset0:0 offset1:16
	ds_read2_b64 v[174:177], v59 offset0:32 offset1:48
	ds_read2_b64 v[32:35], v59 offset0:64 offset1:80
	ds_read2_b64 v[36:39], v59 offset0:96 offset1:112
	ds_read2_b64 v[40:43], v59 offset0:128 offset1:144
	ds_read2_b64 v[44:47], v59 offset0:160 offset1:176
	ds_read2_b64 v[48:51], v59 offset0:192 offset1:208
	ds_read2_b64 v[52:55], v59 offset0:224 offset1:240
	s_waitcnt lgkmcnt(7)
	v_mul_f32_e32 v27, v165, v187
	v_mul_f32_e32 v29, v165, v186
	v_fma_f32 v100, v164, v186, -v27
	v_fma_f32 v101, v164, v187, v29
	v_mul_f32_e32 v30, v167, v189
	v_mul_f32_e32 v31, v167, v188
	v_fma_f32 v102, v166, v188, -v30
	v_fma_f32 v103, v166, v189, v31
	s_waitcnt lgkmcnt(6)
	v_mul_f32_e32 v27, v195, v175
	v_mul_f32_e32 v29, v195, v174
	v_fma_f32 v104, v194, v174, -v27
	v_fma_f32 v105, v194, v175, v29
	v_mul_f32_e32 v30, v197, v177
	v_mul_f32_e32 v31, v197, v176
	v_fma_f32 v106, v196, v176, -v30
	v_fma_f32 v107, v196, v177, v31
	s_waitcnt lgkmcnt(5)
	v_mul_f32_e32 v27, v199, v33
	v_mul_f32_e32 v29, v199, v32
	v_fma_f32 v108, v198, v32, -v27
	v_fma_f32 v109, v198, v33, v29
	v_mul_f32_e32 v30, v201, v35
	v_mul_f32_e32 v31, v201, v34
	v_fma_f32 v110, v200, v34, -v30
	v_fma_f32 v111, v200, v35, v31
	s_waitcnt lgkmcnt(4)
	v_mul_f32_e32 v27, v203, v37
	v_mul_f32_e32 v29, v203, v36
	v_fma_f32 v112, v202, v36, -v27
	v_fma_f32 v113, v202, v37, v29
	v_mul_f32_e32 v30, v205, v39
	v_mul_f32_e32 v31, v205, v38
	v_fma_f32 v114, v204, v38, -v30
	v_fma_f32 v115, v204, v39, v31
	s_waitcnt lgkmcnt(3)
	v_mul_f32_e32 v27, v207, v41
	v_mul_f32_e32 v29, v207, v40
	v_fma_f32 v116, v206, v40, -v27
	v_fma_f32 v117, v206, v41, v29
	v_mul_f32_e32 v30, v209, v43
	v_mul_f32_e32 v31, v209, v42
	v_fma_f32 v118, v208, v42, -v30
	v_fma_f32 v119, v208, v43, v31
	s_waitcnt lgkmcnt(2)
	v_mul_f32_e32 v27, v211, v45
	v_mul_f32_e32 v29, v211, v44
	v_fma_f32 v120, v210, v44, -v27
	v_fma_f32 v121, v210, v45, v29
	v_mul_f32_e32 v30, v213, v47
	v_mul_f32_e32 v31, v213, v46
	v_fma_f32 v122, v212, v46, -v30
	v_fma_f32 v123, v212, v47, v31
	s_waitcnt lgkmcnt(1)
	v_mul_f32_e32 v27, v215, v49
	v_mul_f32_e32 v29, v215, v48
	v_fma_f32 v124, v214, v48, -v27
	v_fma_f32 v125, v214, v49, v29
	v_mul_f32_e32 v30, v217, v51
	v_mul_f32_e32 v31, v217, v50
	v_fma_f32 v126, v216, v50, -v30
	v_fma_f32 v127, v216, v51, v31
	s_waitcnt lgkmcnt(0)
	v_mul_f32_e32 v27, v219, v53
	v_mul_f32_e32 v29, v219, v52
	v_fma_f32 v128, v218, v52, -v27
	v_fma_f32 v129, v218, v53, v29
	v_mul_f32_e32 v30, v221, v55
	v_mul_f32_e32 v31, v221, v54
	v_fma_f32 v130, v220, v54, -v30
	v_fma_f32 v131, v220, v55, v31
	ds_read_b128 v[164:167], v60 offset:0
	ds_read_b128 v[194:197], v60 offset:512
	ds_read_b128 v[198:201], v60 offset:16
	ds_read_b128 v[202:205], v60 offset:528
	ds_read_b128 v[206:209], v60 offset:32
	ds_read_b128 v[210:213], v60 offset:544
	ds_read_b128 v[214:217], v60 offset:48
	ds_read_b128 v[218:221], v60 offset:560
	ds_read_b128 v[186:189], v60 offset:64
	ds_read_b128 v[174:177], v60 offset:576
	ds_read_b128 v[32:35], v60 offset:80
	ds_read_b128 v[36:39], v60 offset:592
	ds_read_b128 v[40:43], v60 offset:96
	ds_read_b128 v[44:47], v60 offset:608
	ds_read_b128 v[48:51], v60 offset:112
	ds_read_b128 v[52:55], v60 offset:624
	s_waitcnt lgkmcnt(14)
	v_pk_fma_f32 v[132:133], v[164:165], v[68:69], v[132:133] neg_hi:[1,0,0]
	v_pk_fma_f32 v[134:135], v[194:195], v[68:69], v[134:135] neg_hi:[1,0,0]
	v_pk_fma_f32 v[132:133], v[166:167], v[70:71], v[132:133] neg_hi:[1,0,0]
	v_pk_fma_f32 v[134:135], v[196:197], v[70:71], v[134:135] neg_hi:[1,0,0]
	s_waitcnt lgkmcnt(12)
	v_pk_fma_f32 v[132:133], v[198:199], v[72:73], v[132:133] neg_hi:[1,0,0]
	v_pk_fma_f32 v[134:135], v[202:203], v[72:73], v[134:135] neg_hi:[1,0,0]
	v_pk_fma_f32 v[132:133], v[200:201], v[74:75], v[132:133] neg_hi:[1,0,0]
	v_pk_fma_f32 v[134:135], v[204:205], v[74:75], v[134:135] neg_hi:[1,0,0]
	s_waitcnt lgkmcnt(10)
	v_pk_fma_f32 v[132:133], v[206:207], v[76:77], v[132:133] neg_hi:[1,0,0]
	v_pk_fma_f32 v[134:135], v[210:211], v[76:77], v[134:135] neg_hi:[1,0,0]
	v_pk_fma_f32 v[132:133], v[208:209], v[78:79], v[132:133] neg_hi:[1,0,0]
	v_pk_fma_f32 v[134:135], v[212:213], v[78:79], v[134:135] neg_hi:[1,0,0]
	s_waitcnt lgkmcnt(8)
	v_pk_fma_f32 v[132:133], v[214:215], v[80:81], v[132:133] neg_hi:[1,0,0]
	v_pk_fma_f32 v[134:135], v[218:219], v[80:81], v[134:135] neg_hi:[1,0,0]
	v_pk_fma_f32 v[132:133], v[216:217], v[82:83], v[132:133] neg_hi:[1,0,0]
	v_pk_fma_f32 v[134:135], v[220:221], v[82:83], v[134:135] neg_hi:[1,0,0]
	ds_read_b128 v[164:167], v60 offset:128
	ds_read_b128 v[194:197], v60 offset:640
	ds_read_b128 v[198:201], v60 offset:144
	ds_read_b128 v[202:205], v60 offset:656
	ds_read_b128 v[206:209], v60 offset:160
	ds_read_b128 v[210:213], v60 offset:672
	ds_read_b128 v[214:217], v60 offset:176
	ds_read_b128 v[218:221], v60 offset:688
	s_waitcnt lgkmcnt(14)
	v_pk_fma_f32 v[132:133], v[186:187], v[84:85], v[132:133] neg_hi:[1,0,0]
	v_pk_fma_f32 v[134:135], v[174:175], v[84:85], v[134:135] neg_hi:[1,0,0]
	v_pk_fma_f32 v[132:133], v[188:189], v[86:87], v[132:133] neg_hi:[1,0,0]
	v_pk_fma_f32 v[134:135], v[176:177], v[86:87], v[134:135] neg_hi:[1,0,0]
	s_waitcnt lgkmcnt(12)
	v_pk_fma_f32 v[132:133], v[32:33], v[88:89], v[132:133] neg_hi:[1,0,0]
	v_pk_fma_f32 v[134:135], v[36:37], v[88:89], v[134:135] neg_hi:[1,0,0]
	v_pk_fma_f32 v[132:133], v[34:35], v[90:91], v[132:133] neg_hi:[1,0,0]
	v_pk_fma_f32 v[134:135], v[38:39], v[90:91], v[134:135] neg_hi:[1,0,0]
	s_waitcnt lgkmcnt(10)
	v_pk_fma_f32 v[132:133], v[40:41], v[92:93], v[132:133] neg_hi:[1,0,0]
	v_pk_fma_f32 v[134:135], v[44:45], v[92:93], v[134:135] neg_hi:[1,0,0]
	v_pk_fma_f32 v[132:133], v[42:43], v[94:95], v[132:133] neg_hi:[1,0,0]
	v_pk_fma_f32 v[134:135], v[46:47], v[94:95], v[134:135] neg_hi:[1,0,0]
	s_waitcnt lgkmcnt(8)
	v_pk_fma_f32 v[132:133], v[48:49], v[96:97], v[132:133] neg_hi:[1,0,0]
	v_pk_fma_f32 v[134:135], v[52:53], v[96:97], v[134:135] neg_hi:[1,0,0]
	v_pk_fma_f32 v[132:133], v[50:51], v[98:99], v[132:133] neg_hi:[1,0,0]
	v_pk_fma_f32 v[134:135], v[54:55], v[98:99], v[134:135] neg_hi:[1,0,0]
	ds_read_b128 v[186:189], v60 offset:192
	ds_read_b128 v[174:177], v60 offset:704
	ds_read_b128 v[32:35], v60 offset:208
	ds_read_b128 v[36:39], v60 offset:720
	ds_read_b128 v[40:43], v60 offset:224
	ds_read_b128 v[44:47], v60 offset:736
	ds_read_b128 v[48:51], v60 offset:240
	ds_read_b128 v[52:55], v60 offset:752
	s_waitcnt lgkmcnt(14)
	v_pk_fma_f32 v[132:133], v[164:165], v[100:101], v[132:133] neg_hi:[1,0,0]
	v_pk_fma_f32 v[134:135], v[194:195], v[100:101], v[134:135] neg_hi:[1,0,0]
	v_pk_fma_f32 v[132:133], v[166:167], v[102:103], v[132:133] neg_hi:[1,0,0]
	v_pk_fma_f32 v[134:135], v[196:197], v[102:103], v[134:135] neg_hi:[1,0,0]
	s_waitcnt lgkmcnt(12)
	v_pk_fma_f32 v[132:133], v[198:199], v[104:105], v[132:133] neg_hi:[1,0,0]
	v_pk_fma_f32 v[134:135], v[202:203], v[104:105], v[134:135] neg_hi:[1,0,0]
	v_pk_fma_f32 v[132:133], v[200:201], v[106:107], v[132:133] neg_hi:[1,0,0]
	v_pk_fma_f32 v[134:135], v[204:205], v[106:107], v[134:135] neg_hi:[1,0,0]
	s_waitcnt lgkmcnt(10)
	v_pk_fma_f32 v[132:133], v[206:207], v[108:109], v[132:133] neg_hi:[1,0,0]
	v_pk_fma_f32 v[134:135], v[210:211], v[108:109], v[134:135] neg_hi:[1,0,0]
	v_pk_fma_f32 v[132:133], v[208:209], v[110:111], v[132:133] neg_hi:[1,0,0]
	v_pk_fma_f32 v[134:135], v[212:213], v[110:111], v[134:135] neg_hi:[1,0,0]
	s_waitcnt lgkmcnt(8)
	v_pk_fma_f32 v[132:133], v[214:215], v[112:113], v[132:133] neg_hi:[1,0,0]
	v_pk_fma_f32 v[134:135], v[218:219], v[112:113], v[134:135] neg_hi:[1,0,0]
	v_pk_fma_f32 v[132:133], v[216:217], v[114:115], v[132:133] neg_hi:[1,0,0]
	v_pk_fma_f32 v[134:135], v[220:221], v[114:115], v[134:135] neg_hi:[1,0,0]
	ds_read_b128 v[164:167], v60 offset:1024
	ds_read_b128 v[194:197], v60 offset:1536
	ds_read_b128 v[198:201], v60 offset:1040
	ds_read_b128 v[202:205], v60 offset:1552
	ds_read_b128 v[206:209], v60 offset:1056
	ds_read_b128 v[210:213], v60 offset:1568
	ds_read_b128 v[214:217], v60 offset:1072
	ds_read_b128 v[218:221], v60 offset:1584
	s_waitcnt lgkmcnt(14)
	v_pk_fma_f32 v[132:133], v[186:187], v[116:117], v[132:133] neg_hi:[1,0,0]
	v_pk_fma_f32 v[134:135], v[174:175], v[116:117], v[134:135] neg_hi:[1,0,0]
	v_pk_fma_f32 v[132:133], v[188:189], v[118:119], v[132:133] neg_hi:[1,0,0]
	v_pk_fma_f32 v[134:135], v[176:177], v[118:119], v[134:135] neg_hi:[1,0,0]
	s_waitcnt lgkmcnt(12)
	v_pk_fma_f32 v[132:133], v[32:33], v[120:121], v[132:133] neg_hi:[1,0,0]
	v_pk_fma_f32 v[134:135], v[36:37], v[120:121], v[134:135] neg_hi:[1,0,0]
	v_pk_fma_f32 v[132:133], v[34:35], v[122:123], v[132:133] neg_hi:[1,0,0]
	v_pk_fma_f32 v[134:135], v[38:39], v[122:123], v[134:135] neg_hi:[1,0,0]
	s_waitcnt lgkmcnt(10)
	v_pk_fma_f32 v[132:133], v[40:41], v[124:125], v[132:133] neg_hi:[1,0,0]
	v_pk_fma_f32 v[134:135], v[44:45], v[124:125], v[134:135] neg_hi:[1,0,0]
	v_pk_fma_f32 v[132:133], v[42:43], v[126:127], v[132:133] neg_hi:[1,0,0]
	v_pk_fma_f32 v[134:135], v[46:47], v[126:127], v[134:135] neg_hi:[1,0,0]
	s_waitcnt lgkmcnt(8)
	v_pk_fma_f32 v[132:133], v[48:49], v[128:129], v[132:133] neg_hi:[1,0,0]
	v_pk_fma_f32 v[134:135], v[52:53], v[128:129], v[134:135] neg_hi:[1,0,0]
	v_pk_fma_f32 v[132:133], v[50:51], v[130:131], v[132:133] neg_hi:[1,0,0]
	v_pk_fma_f32 v[134:135], v[54:55], v[130:131], v[134:135] neg_hi:[1,0,0]
	ds_read_b128 v[186:189], v60 offset:1088
	ds_read_b128 v[174:177], v60 offset:1600
	ds_read_b128 v[32:35], v60 offset:1104
	ds_read_b128 v[36:39], v60 offset:1616
	ds_read_b128 v[40:43], v60 offset:1120
	ds_read_b128 v[44:47], v60 offset:1632
	ds_read_b128 v[48:51], v60 offset:1136
	ds_read_b128 v[52:55], v60 offset:1648
	s_waitcnt lgkmcnt(14)
	v_pk_fma_f32 v[136:137], v[164:165], v[68:69], v[136:137] neg_hi:[1,0,0]
	v_pk_fma_f32 v[138:139], v[194:195], v[68:69], v[138:139] neg_hi:[1,0,0]
	v_pk_fma_f32 v[136:137], v[166:167], v[70:71], v[136:137] neg_hi:[1,0,0]
	v_pk_fma_f32 v[138:139], v[196:197], v[70:71], v[138:139] neg_hi:[1,0,0]
	s_waitcnt lgkmcnt(12)
	v_pk_fma_f32 v[136:137], v[198:199], v[72:73], v[136:137] neg_hi:[1,0,0]
	v_pk_fma_f32 v[138:139], v[202:203], v[72:73], v[138:139] neg_hi:[1,0,0]
	v_pk_fma_f32 v[136:137], v[200:201], v[74:75], v[136:137] neg_hi:[1,0,0]
	v_pk_fma_f32 v[138:139], v[204:205], v[74:75], v[138:139] neg_hi:[1,0,0]
	s_waitcnt lgkmcnt(10)
	v_pk_fma_f32 v[136:137], v[206:207], v[76:77], v[136:137] neg_hi:[1,0,0]
	v_pk_fma_f32 v[138:139], v[210:211], v[76:77], v[138:139] neg_hi:[1,0,0]
	v_pk_fma_f32 v[136:137], v[208:209], v[78:79], v[136:137] neg_hi:[1,0,0]
	v_pk_fma_f32 v[138:139], v[212:213], v[78:79], v[138:139] neg_hi:[1,0,0]
	s_waitcnt lgkmcnt(8)
	v_pk_fma_f32 v[136:137], v[214:215], v[80:81], v[136:137] neg_hi:[1,0,0]
	v_pk_fma_f32 v[138:139], v[218:219], v[80:81], v[138:139] neg_hi:[1,0,0]
	v_pk_fma_f32 v[136:137], v[216:217], v[82:83], v[136:137] neg_hi:[1,0,0]
	v_pk_fma_f32 v[138:139], v[220:221], v[82:83], v[138:139] neg_hi:[1,0,0]
	ds_read_b128 v[164:167], v60 offset:1152
	ds_read_b128 v[194:197], v60 offset:1664
	ds_read_b128 v[198:201], v60 offset:1168
	ds_read_b128 v[202:205], v60 offset:1680
	ds_read_b128 v[206:209], v60 offset:1184
	ds_read_b128 v[210:213], v60 offset:1696
	ds_read_b128 v[214:217], v60 offset:1200
	ds_read_b128 v[218:221], v60 offset:1712
	s_waitcnt lgkmcnt(14)
	v_pk_fma_f32 v[136:137], v[186:187], v[84:85], v[136:137] neg_hi:[1,0,0]
	v_pk_fma_f32 v[138:139], v[174:175], v[84:85], v[138:139] neg_hi:[1,0,0]
	v_pk_fma_f32 v[136:137], v[188:189], v[86:87], v[136:137] neg_hi:[1,0,0]
	v_pk_fma_f32 v[138:139], v[176:177], v[86:87], v[138:139] neg_hi:[1,0,0]
	s_waitcnt lgkmcnt(12)
	v_pk_fma_f32 v[136:137], v[32:33], v[88:89], v[136:137] neg_hi:[1,0,0]
	v_pk_fma_f32 v[138:139], v[36:37], v[88:89], v[138:139] neg_hi:[1,0,0]
	v_pk_fma_f32 v[136:137], v[34:35], v[90:91], v[136:137] neg_hi:[1,0,0]
	v_pk_fma_f32 v[138:139], v[38:39], v[90:91], v[138:139] neg_hi:[1,0,0]
	s_waitcnt lgkmcnt(10)
	v_pk_fma_f32 v[136:137], v[40:41], v[92:93], v[136:137] neg_hi:[1,0,0]
	v_pk_fma_f32 v[138:139], v[44:45], v[92:93], v[138:139] neg_hi:[1,0,0]
	v_pk_fma_f32 v[136:137], v[42:43], v[94:95], v[136:137] neg_hi:[1,0,0]
	v_pk_fma_f32 v[138:139], v[46:47], v[94:95], v[138:139] neg_hi:[1,0,0]
	s_waitcnt lgkmcnt(8)
	v_pk_fma_f32 v[136:137], v[48:49], v[96:97], v[136:137] neg_hi:[1,0,0]
	v_pk_fma_f32 v[138:139], v[52:53], v[96:97], v[138:139] neg_hi:[1,0,0]
	v_pk_fma_f32 v[136:137], v[50:51], v[98:99], v[136:137] neg_hi:[1,0,0]
	v_pk_fma_f32 v[138:139], v[54:55], v[98:99], v[138:139] neg_hi:[1,0,0]
	ds_read_b128 v[186:189], v60 offset:1216
	ds_read_b128 v[174:177], v60 offset:1728
	ds_read_b128 v[32:35], v60 offset:1232
	ds_read_b128 v[36:39], v60 offset:1744
	ds_read_b128 v[40:43], v60 offset:1248
	ds_read_b128 v[44:47], v60 offset:1760
	ds_read_b128 v[48:51], v60 offset:1264
	ds_read_b128 v[52:55], v60 offset:1776
	s_waitcnt lgkmcnt(14)
	v_pk_fma_f32 v[136:137], v[164:165], v[100:101], v[136:137] neg_hi:[1,0,0]
	v_pk_fma_f32 v[138:139], v[194:195], v[100:101], v[138:139] neg_hi:[1,0,0]
	v_pk_fma_f32 v[136:137], v[166:167], v[102:103], v[136:137] neg_hi:[1,0,0]
	v_pk_fma_f32 v[138:139], v[196:197], v[102:103], v[138:139] neg_hi:[1,0,0]
	s_waitcnt lgkmcnt(12)
	v_pk_fma_f32 v[136:137], v[198:199], v[104:105], v[136:137] neg_hi:[1,0,0]
	v_pk_fma_f32 v[138:139], v[202:203], v[104:105], v[138:139] neg_hi:[1,0,0]
	v_pk_fma_f32 v[136:137], v[200:201], v[106:107], v[136:137] neg_hi:[1,0,0]
	v_pk_fma_f32 v[138:139], v[204:205], v[106:107], v[138:139] neg_hi:[1,0,0]
	s_waitcnt lgkmcnt(10)
	v_pk_fma_f32 v[136:137], v[206:207], v[108:109], v[136:137] neg_hi:[1,0,0]
	v_pk_fma_f32 v[138:139], v[210:211], v[108:109], v[138:139] neg_hi:[1,0,0]
	v_pk_fma_f32 v[136:137], v[208:209], v[110:111], v[136:137] neg_hi:[1,0,0]
	v_pk_fma_f32 v[138:139], v[212:213], v[110:111], v[138:139] neg_hi:[1,0,0]
	s_waitcnt lgkmcnt(8)
	v_pk_fma_f32 v[136:137], v[214:215], v[112:113], v[136:137] neg_hi:[1,0,0]
	v_pk_fma_f32 v[138:139], v[218:219], v[112:113], v[138:139] neg_hi:[1,0,0]
	v_pk_fma_f32 v[136:137], v[216:217], v[114:115], v[136:137] neg_hi:[1,0,0]
	v_pk_fma_f32 v[138:139], v[220:221], v[114:115], v[138:139] neg_hi:[1,0,0]
	ds_read_b128 v[164:167], v60 offset:2048
	ds_read_b128 v[194:197], v60 offset:2560
	ds_read_b128 v[198:201], v60 offset:2064
	ds_read_b128 v[202:205], v60 offset:2576
	ds_read_b128 v[206:209], v60 offset:2080
	ds_read_b128 v[210:213], v60 offset:2592
	ds_read_b128 v[214:217], v60 offset:2096
	ds_read_b128 v[218:221], v60 offset:2608
	s_waitcnt lgkmcnt(14)
	v_pk_fma_f32 v[136:137], v[186:187], v[116:117], v[136:137] neg_hi:[1,0,0]
	v_pk_fma_f32 v[138:139], v[174:175], v[116:117], v[138:139] neg_hi:[1,0,0]
	v_pk_fma_f32 v[136:137], v[188:189], v[118:119], v[136:137] neg_hi:[1,0,0]
	v_pk_fma_f32 v[138:139], v[176:177], v[118:119], v[138:139] neg_hi:[1,0,0]
	s_waitcnt lgkmcnt(12)
	v_pk_fma_f32 v[136:137], v[32:33], v[120:121], v[136:137] neg_hi:[1,0,0]
	v_pk_fma_f32 v[138:139], v[36:37], v[120:121], v[138:139] neg_hi:[1,0,0]
	v_pk_fma_f32 v[136:137], v[34:35], v[122:123], v[136:137] neg_hi:[1,0,0]
	v_pk_fma_f32 v[138:139], v[38:39], v[122:123], v[138:139] neg_hi:[1,0,0]
	s_waitcnt lgkmcnt(10)
	v_pk_fma_f32 v[136:137], v[40:41], v[124:125], v[136:137] neg_hi:[1,0,0]
	v_pk_fma_f32 v[138:139], v[44:45], v[124:125], v[138:139] neg_hi:[1,0,0]
	v_pk_fma_f32 v[136:137], v[42:43], v[126:127], v[136:137] neg_hi:[1,0,0]
	v_pk_fma_f32 v[138:139], v[46:47], v[126:127], v[138:139] neg_hi:[1,0,0]
	s_waitcnt lgkmcnt(8)
	v_pk_fma_f32 v[136:137], v[48:49], v[128:129], v[136:137] neg_hi:[1,0,0]
	v_pk_fma_f32 v[138:139], v[52:53], v[128:129], v[138:139] neg_hi:[1,0,0]
	v_pk_fma_f32 v[136:137], v[50:51], v[130:131], v[136:137] neg_hi:[1,0,0]
	v_pk_fma_f32 v[138:139], v[54:55], v[130:131], v[138:139] neg_hi:[1,0,0]
	ds_read_b128 v[186:189], v60 offset:2112
	ds_read_b128 v[174:177], v60 offset:2624
	ds_read_b128 v[32:35], v60 offset:2128
	ds_read_b128 v[36:39], v60 offset:2640
	ds_read_b128 v[40:43], v60 offset:2144
	ds_read_b128 v[44:47], v60 offset:2656
	ds_read_b128 v[48:51], v60 offset:2160
	ds_read_b128 v[52:55], v60 offset:2672
	s_waitcnt lgkmcnt(14)
	v_pk_fma_f32 v[140:141], v[164:165], v[68:69], v[140:141] neg_hi:[1,0,0]
	v_pk_fma_f32 v[142:143], v[194:195], v[68:69], v[142:143] neg_hi:[1,0,0]
	v_pk_fma_f32 v[140:141], v[166:167], v[70:71], v[140:141] neg_hi:[1,0,0]
	v_pk_fma_f32 v[142:143], v[196:197], v[70:71], v[142:143] neg_hi:[1,0,0]
	s_waitcnt lgkmcnt(12)
	v_pk_fma_f32 v[140:141], v[198:199], v[72:73], v[140:141] neg_hi:[1,0,0]
	v_pk_fma_f32 v[142:143], v[202:203], v[72:73], v[142:143] neg_hi:[1,0,0]
	v_pk_fma_f32 v[140:141], v[200:201], v[74:75], v[140:141] neg_hi:[1,0,0]
	v_pk_fma_f32 v[142:143], v[204:205], v[74:75], v[142:143] neg_hi:[1,0,0]
	s_waitcnt lgkmcnt(10)
	v_pk_fma_f32 v[140:141], v[206:207], v[76:77], v[140:141] neg_hi:[1,0,0]
	v_pk_fma_f32 v[142:143], v[210:211], v[76:77], v[142:143] neg_hi:[1,0,0]
	v_pk_fma_f32 v[140:141], v[208:209], v[78:79], v[140:141] neg_hi:[1,0,0]
	v_pk_fma_f32 v[142:143], v[212:213], v[78:79], v[142:143] neg_hi:[1,0,0]
	s_waitcnt lgkmcnt(8)
	v_pk_fma_f32 v[140:141], v[214:215], v[80:81], v[140:141] neg_hi:[1,0,0]
	v_pk_fma_f32 v[142:143], v[218:219], v[80:81], v[142:143] neg_hi:[1,0,0]
	v_pk_fma_f32 v[140:141], v[216:217], v[82:83], v[140:141] neg_hi:[1,0,0]
	v_pk_fma_f32 v[142:143], v[220:221], v[82:83], v[142:143] neg_hi:[1,0,0]
	ds_read_b128 v[164:167], v60 offset:2176
	ds_read_b128 v[194:197], v60 offset:2688
	ds_read_b128 v[198:201], v60 offset:2192
	ds_read_b128 v[202:205], v60 offset:2704
	ds_read_b128 v[206:209], v60 offset:2208
	ds_read_b128 v[210:213], v60 offset:2720
	ds_read_b128 v[214:217], v60 offset:2224
	ds_read_b128 v[218:221], v60 offset:2736
	s_waitcnt lgkmcnt(14)
	v_pk_fma_f32 v[140:141], v[186:187], v[84:85], v[140:141] neg_hi:[1,0,0]
	v_pk_fma_f32 v[142:143], v[174:175], v[84:85], v[142:143] neg_hi:[1,0,0]
	v_pk_fma_f32 v[140:141], v[188:189], v[86:87], v[140:141] neg_hi:[1,0,0]
	v_pk_fma_f32 v[142:143], v[176:177], v[86:87], v[142:143] neg_hi:[1,0,0]
	s_waitcnt lgkmcnt(12)
	v_pk_fma_f32 v[140:141], v[32:33], v[88:89], v[140:141] neg_hi:[1,0,0]
	v_pk_fma_f32 v[142:143], v[36:37], v[88:89], v[142:143] neg_hi:[1,0,0]
	v_pk_fma_f32 v[140:141], v[34:35], v[90:91], v[140:141] neg_hi:[1,0,0]
	v_pk_fma_f32 v[142:143], v[38:39], v[90:91], v[142:143] neg_hi:[1,0,0]
	s_waitcnt lgkmcnt(10)
	v_pk_fma_f32 v[140:141], v[40:41], v[92:93], v[140:141] neg_hi:[1,0,0]
	v_pk_fma_f32 v[142:143], v[44:45], v[92:93], v[142:143] neg_hi:[1,0,0]
	v_pk_fma_f32 v[140:141], v[42:43], v[94:95], v[140:141] neg_hi:[1,0,0]
	v_pk_fma_f32 v[142:143], v[46:47], v[94:95], v[142:143] neg_hi:[1,0,0]
	s_waitcnt lgkmcnt(8)
	v_pk_fma_f32 v[140:141], v[48:49], v[96:97], v[140:141] neg_hi:[1,0,0]
	v_pk_fma_f32 v[142:143], v[52:53], v[96:97], v[142:143] neg_hi:[1,0,0]
	v_pk_fma_f32 v[140:141], v[50:51], v[98:99], v[140:141] neg_hi:[1,0,0]
	v_pk_fma_f32 v[142:143], v[54:55], v[98:99], v[142:143] neg_hi:[1,0,0]
	ds_read_b128 v[186:189], v60 offset:2240
	ds_read_b128 v[174:177], v60 offset:2752
	ds_read_b128 v[32:35], v60 offset:2256
	ds_read_b128 v[36:39], v60 offset:2768
	ds_read_b128 v[40:43], v60 offset:2272
	ds_read_b128 v[44:47], v60 offset:2784
	ds_read_b128 v[48:51], v60 offset:2288
	ds_read_b128 v[52:55], v60 offset:2800
	s_waitcnt lgkmcnt(14)
	v_pk_fma_f32 v[140:141], v[164:165], v[100:101], v[140:141] neg_hi:[1,0,0]
	v_pk_fma_f32 v[142:143], v[194:195], v[100:101], v[142:143] neg_hi:[1,0,0]
	v_pk_fma_f32 v[140:141], v[166:167], v[102:103], v[140:141] neg_hi:[1,0,0]
	v_pk_fma_f32 v[142:143], v[196:197], v[102:103], v[142:143] neg_hi:[1,0,0]
	s_waitcnt lgkmcnt(12)
	v_pk_fma_f32 v[140:141], v[198:199], v[104:105], v[140:141] neg_hi:[1,0,0]
	v_pk_fma_f32 v[142:143], v[202:203], v[104:105], v[142:143] neg_hi:[1,0,0]
	v_pk_fma_f32 v[140:141], v[200:201], v[106:107], v[140:141] neg_hi:[1,0,0]
	v_pk_fma_f32 v[142:143], v[204:205], v[106:107], v[142:143] neg_hi:[1,0,0]
	s_waitcnt lgkmcnt(10)
	v_pk_fma_f32 v[140:141], v[206:207], v[108:109], v[140:141] neg_hi:[1,0,0]
	v_pk_fma_f32 v[142:143], v[210:211], v[108:109], v[142:143] neg_hi:[1,0,0]
	v_pk_fma_f32 v[140:141], v[208:209], v[110:111], v[140:141] neg_hi:[1,0,0]
	v_pk_fma_f32 v[142:143], v[212:213], v[110:111], v[142:143] neg_hi:[1,0,0]
	s_waitcnt lgkmcnt(8)
	v_pk_fma_f32 v[140:141], v[214:215], v[112:113], v[140:141] neg_hi:[1,0,0]
	v_pk_fma_f32 v[142:143], v[218:219], v[112:113], v[142:143] neg_hi:[1,0,0]
	v_pk_fma_f32 v[140:141], v[216:217], v[114:115], v[140:141] neg_hi:[1,0,0]
	v_pk_fma_f32 v[142:143], v[220:221], v[114:115], v[142:143] neg_hi:[1,0,0]
	ds_read_b128 v[164:167], v60 offset:3072
	ds_read_b128 v[194:197], v60 offset:3584
	ds_read_b128 v[198:201], v60 offset:3088
	ds_read_b128 v[202:205], v60 offset:3600
	ds_read_b128 v[206:209], v60 offset:3104
	ds_read_b128 v[210:213], v60 offset:3616
	ds_read_b128 v[214:217], v60 offset:3120
	ds_read_b128 v[218:221], v60 offset:3632
	s_waitcnt lgkmcnt(14)
	v_pk_fma_f32 v[140:141], v[186:187], v[116:117], v[140:141] neg_hi:[1,0,0]
	v_pk_fma_f32 v[142:143], v[174:175], v[116:117], v[142:143] neg_hi:[1,0,0]
	v_pk_fma_f32 v[140:141], v[188:189], v[118:119], v[140:141] neg_hi:[1,0,0]
	v_pk_fma_f32 v[142:143], v[176:177], v[118:119], v[142:143] neg_hi:[1,0,0]
	s_waitcnt lgkmcnt(12)
	v_pk_fma_f32 v[140:141], v[32:33], v[120:121], v[140:141] neg_hi:[1,0,0]
	v_pk_fma_f32 v[142:143], v[36:37], v[120:121], v[142:143] neg_hi:[1,0,0]
	v_pk_fma_f32 v[140:141], v[34:35], v[122:123], v[140:141] neg_hi:[1,0,0]
	v_pk_fma_f32 v[142:143], v[38:39], v[122:123], v[142:143] neg_hi:[1,0,0]
	s_waitcnt lgkmcnt(10)
	v_pk_fma_f32 v[140:141], v[40:41], v[124:125], v[140:141] neg_hi:[1,0,0]
	v_pk_fma_f32 v[142:143], v[44:45], v[124:125], v[142:143] neg_hi:[1,0,0]
	v_pk_fma_f32 v[140:141], v[42:43], v[126:127], v[140:141] neg_hi:[1,0,0]
	v_pk_fma_f32 v[142:143], v[46:47], v[126:127], v[142:143] neg_hi:[1,0,0]
	s_waitcnt lgkmcnt(8)
	v_pk_fma_f32 v[140:141], v[48:49], v[128:129], v[140:141] neg_hi:[1,0,0]
	v_pk_fma_f32 v[142:143], v[52:53], v[128:129], v[142:143] neg_hi:[1,0,0]
	v_pk_fma_f32 v[140:141], v[50:51], v[130:131], v[140:141] neg_hi:[1,0,0]
	v_pk_fma_f32 v[142:143], v[54:55], v[130:131], v[142:143] neg_hi:[1,0,0]
	ds_read_b128 v[186:189], v60 offset:3136
	ds_read_b128 v[174:177], v60 offset:3648
	ds_read_b128 v[32:35], v60 offset:3152
	ds_read_b128 v[36:39], v60 offset:3664
	ds_read_b128 v[40:43], v60 offset:3168
	ds_read_b128 v[44:47], v60 offset:3680
	ds_read_b128 v[48:51], v60 offset:3184
	ds_read_b128 v[52:55], v60 offset:3696
	s_waitcnt lgkmcnt(14)
	v_pk_fma_f32 v[144:145], v[164:165], v[68:69], v[144:145] neg_hi:[1,0,0]
	v_pk_fma_f32 v[146:147], v[194:195], v[68:69], v[146:147] neg_hi:[1,0,0]
	v_pk_fma_f32 v[144:145], v[166:167], v[70:71], v[144:145] neg_hi:[1,0,0]
	v_pk_fma_f32 v[146:147], v[196:197], v[70:71], v[146:147] neg_hi:[1,0,0]
	s_waitcnt lgkmcnt(12)
	v_pk_fma_f32 v[144:145], v[198:199], v[72:73], v[144:145] neg_hi:[1,0,0]
	v_pk_fma_f32 v[146:147], v[202:203], v[72:73], v[146:147] neg_hi:[1,0,0]
	v_pk_fma_f32 v[144:145], v[200:201], v[74:75], v[144:145] neg_hi:[1,0,0]
	v_pk_fma_f32 v[146:147], v[204:205], v[74:75], v[146:147] neg_hi:[1,0,0]
	s_waitcnt lgkmcnt(10)
	v_pk_fma_f32 v[144:145], v[206:207], v[76:77], v[144:145] neg_hi:[1,0,0]
	v_pk_fma_f32 v[146:147], v[210:211], v[76:77], v[146:147] neg_hi:[1,0,0]
	v_pk_fma_f32 v[144:145], v[208:209], v[78:79], v[144:145] neg_hi:[1,0,0]
	v_pk_fma_f32 v[146:147], v[212:213], v[78:79], v[146:147] neg_hi:[1,0,0]
	s_waitcnt lgkmcnt(8)
	v_pk_fma_f32 v[144:145], v[214:215], v[80:81], v[144:145] neg_hi:[1,0,0]
	v_pk_fma_f32 v[146:147], v[218:219], v[80:81], v[146:147] neg_hi:[1,0,0]
	v_pk_fma_f32 v[144:145], v[216:217], v[82:83], v[144:145] neg_hi:[1,0,0]
	v_pk_fma_f32 v[146:147], v[220:221], v[82:83], v[146:147] neg_hi:[1,0,0]
	ds_read_b128 v[164:167], v60 offset:3200
	ds_read_b128 v[194:197], v60 offset:3712
	ds_read_b128 v[198:201], v60 offset:3216
	ds_read_b128 v[202:205], v60 offset:3728
	ds_read_b128 v[206:209], v60 offset:3232
	ds_read_b128 v[210:213], v60 offset:3744
	ds_read_b128 v[214:217], v60 offset:3248
	ds_read_b128 v[218:221], v60 offset:3760
	s_waitcnt lgkmcnt(14)
	v_pk_fma_f32 v[144:145], v[186:187], v[84:85], v[144:145] neg_hi:[1,0,0]
	v_pk_fma_f32 v[146:147], v[174:175], v[84:85], v[146:147] neg_hi:[1,0,0]
	v_pk_fma_f32 v[144:145], v[188:189], v[86:87], v[144:145] neg_hi:[1,0,0]
	v_pk_fma_f32 v[146:147], v[176:177], v[86:87], v[146:147] neg_hi:[1,0,0]
	s_waitcnt lgkmcnt(12)
	v_pk_fma_f32 v[144:145], v[32:33], v[88:89], v[144:145] neg_hi:[1,0,0]
	v_pk_fma_f32 v[146:147], v[36:37], v[88:89], v[146:147] neg_hi:[1,0,0]
	v_pk_fma_f32 v[144:145], v[34:35], v[90:91], v[144:145] neg_hi:[1,0,0]
	v_pk_fma_f32 v[146:147], v[38:39], v[90:91], v[146:147] neg_hi:[1,0,0]
	s_waitcnt lgkmcnt(10)
	v_pk_fma_f32 v[144:145], v[40:41], v[92:93], v[144:145] neg_hi:[1,0,0]
	v_pk_fma_f32 v[146:147], v[44:45], v[92:93], v[146:147] neg_hi:[1,0,0]
	v_pk_fma_f32 v[144:145], v[42:43], v[94:95], v[144:145] neg_hi:[1,0,0]
	v_pk_fma_f32 v[146:147], v[46:47], v[94:95], v[146:147] neg_hi:[1,0,0]
	s_waitcnt lgkmcnt(8)
	v_pk_fma_f32 v[144:145], v[48:49], v[96:97], v[144:145] neg_hi:[1,0,0]
	v_pk_fma_f32 v[146:147], v[52:53], v[96:97], v[146:147] neg_hi:[1,0,0]
	v_pk_fma_f32 v[144:145], v[50:51], v[98:99], v[144:145] neg_hi:[1,0,0]
	v_pk_fma_f32 v[146:147], v[54:55], v[98:99], v[146:147] neg_hi:[1,0,0]
	ds_read_b128 v[186:189], v60 offset:3264
	ds_read_b128 v[174:177], v60 offset:3776
	ds_read_b128 v[32:35], v60 offset:3280
	ds_read_b128 v[36:39], v60 offset:3792
	ds_read_b128 v[40:43], v60 offset:3296
	ds_read_b128 v[44:47], v60 offset:3808
	ds_read_b128 v[48:51], v60 offset:3312
	ds_read_b128 v[52:55], v60 offset:3824
	s_waitcnt lgkmcnt(14)
	v_pk_fma_f32 v[144:145], v[164:165], v[100:101], v[144:145] neg_hi:[1,0,0]
	v_pk_fma_f32 v[146:147], v[194:195], v[100:101], v[146:147] neg_hi:[1,0,0]
	v_pk_fma_f32 v[144:145], v[166:167], v[102:103], v[144:145] neg_hi:[1,0,0]
	v_pk_fma_f32 v[146:147], v[196:197], v[102:103], v[146:147] neg_hi:[1,0,0]
	s_waitcnt lgkmcnt(12)
	v_pk_fma_f32 v[144:145], v[198:199], v[104:105], v[144:145] neg_hi:[1,0,0]
	v_pk_fma_f32 v[146:147], v[202:203], v[104:105], v[146:147] neg_hi:[1,0,0]
	v_pk_fma_f32 v[144:145], v[200:201], v[106:107], v[144:145] neg_hi:[1,0,0]
	v_pk_fma_f32 v[146:147], v[204:205], v[106:107], v[146:147] neg_hi:[1,0,0]
	s_waitcnt lgkmcnt(10)
	v_pk_fma_f32 v[144:145], v[206:207], v[108:109], v[144:145] neg_hi:[1,0,0]
	v_pk_fma_f32 v[146:147], v[210:211], v[108:109], v[146:147] neg_hi:[1,0,0]
	v_pk_fma_f32 v[144:145], v[208:209], v[110:111], v[144:145] neg_hi:[1,0,0]
	v_pk_fma_f32 v[146:147], v[212:213], v[110:111], v[146:147] neg_hi:[1,0,0]
	s_waitcnt lgkmcnt(8)
	v_pk_fma_f32 v[144:145], v[214:215], v[112:113], v[144:145] neg_hi:[1,0,0]
	v_pk_fma_f32 v[146:147], v[218:219], v[112:113], v[146:147] neg_hi:[1,0,0]
	v_pk_fma_f32 v[144:145], v[216:217], v[114:115], v[144:145] neg_hi:[1,0,0]
	v_pk_fma_f32 v[146:147], v[220:221], v[114:115], v[146:147] neg_hi:[1,0,0]
	ds_read_b128 v[164:167], v60 offset:4096
	ds_read_b128 v[194:197], v60 offset:4608
	ds_read_b128 v[198:201], v60 offset:4112
	ds_read_b128 v[202:205], v60 offset:4624
	ds_read_b128 v[206:209], v60 offset:4128
	ds_read_b128 v[210:213], v60 offset:4640
	ds_read_b128 v[214:217], v60 offset:4144
	ds_read_b128 v[218:221], v60 offset:4656
	s_waitcnt lgkmcnt(14)
	v_pk_fma_f32 v[144:145], v[186:187], v[116:117], v[144:145] neg_hi:[1,0,0]
	v_pk_fma_f32 v[146:147], v[174:175], v[116:117], v[146:147] neg_hi:[1,0,0]
	v_pk_fma_f32 v[144:145], v[188:189], v[118:119], v[144:145] neg_hi:[1,0,0]
	v_pk_fma_f32 v[146:147], v[176:177], v[118:119], v[146:147] neg_hi:[1,0,0]
	s_waitcnt lgkmcnt(12)
	v_pk_fma_f32 v[144:145], v[32:33], v[120:121], v[144:145] neg_hi:[1,0,0]
	v_pk_fma_f32 v[146:147], v[36:37], v[120:121], v[146:147] neg_hi:[1,0,0]
	v_pk_fma_f32 v[144:145], v[34:35], v[122:123], v[144:145] neg_hi:[1,0,0]
	v_pk_fma_f32 v[146:147], v[38:39], v[122:123], v[146:147] neg_hi:[1,0,0]
	s_waitcnt lgkmcnt(10)
	v_pk_fma_f32 v[144:145], v[40:41], v[124:125], v[144:145] neg_hi:[1,0,0]
	v_pk_fma_f32 v[146:147], v[44:45], v[124:125], v[146:147] neg_hi:[1,0,0]
	v_pk_fma_f32 v[144:145], v[42:43], v[126:127], v[144:145] neg_hi:[1,0,0]
	v_pk_fma_f32 v[146:147], v[46:47], v[126:127], v[146:147] neg_hi:[1,0,0]
	s_waitcnt lgkmcnt(8)
	v_pk_fma_f32 v[144:145], v[48:49], v[128:129], v[144:145] neg_hi:[1,0,0]
	v_pk_fma_f32 v[146:147], v[52:53], v[128:129], v[146:147] neg_hi:[1,0,0]
	v_pk_fma_f32 v[144:145], v[50:51], v[130:131], v[144:145] neg_hi:[1,0,0]
	v_pk_fma_f32 v[146:147], v[54:55], v[130:131], v[146:147] neg_hi:[1,0,0]
	ds_read_b128 v[186:189], v60 offset:4160
	ds_read_b128 v[174:177], v60 offset:4672
	ds_read_b128 v[32:35], v60 offset:4176
	ds_read_b128 v[36:39], v60 offset:4688
	ds_read_b128 v[40:43], v60 offset:4192
	ds_read_b128 v[44:47], v60 offset:4704
	ds_read_b128 v[48:51], v60 offset:4208
	ds_read_b128 v[52:55], v60 offset:4720
	s_waitcnt lgkmcnt(14)
	v_pk_fma_f32 v[148:149], v[164:165], v[68:69], v[148:149] neg_hi:[1,0,0]
	v_pk_fma_f32 v[150:151], v[194:195], v[68:69], v[150:151] neg_hi:[1,0,0]
	v_pk_fma_f32 v[148:149], v[166:167], v[70:71], v[148:149] neg_hi:[1,0,0]
	v_pk_fma_f32 v[150:151], v[196:197], v[70:71], v[150:151] neg_hi:[1,0,0]
	s_waitcnt lgkmcnt(12)
	v_pk_fma_f32 v[148:149], v[198:199], v[72:73], v[148:149] neg_hi:[1,0,0]
	v_pk_fma_f32 v[150:151], v[202:203], v[72:73], v[150:151] neg_hi:[1,0,0]
	v_pk_fma_f32 v[148:149], v[200:201], v[74:75], v[148:149] neg_hi:[1,0,0]
	v_pk_fma_f32 v[150:151], v[204:205], v[74:75], v[150:151] neg_hi:[1,0,0]
	s_waitcnt lgkmcnt(10)
	v_pk_fma_f32 v[148:149], v[206:207], v[76:77], v[148:149] neg_hi:[1,0,0]
	v_pk_fma_f32 v[150:151], v[210:211], v[76:77], v[150:151] neg_hi:[1,0,0]
	v_pk_fma_f32 v[148:149], v[208:209], v[78:79], v[148:149] neg_hi:[1,0,0]
	v_pk_fma_f32 v[150:151], v[212:213], v[78:79], v[150:151] neg_hi:[1,0,0]
	s_waitcnt lgkmcnt(8)
	v_pk_fma_f32 v[148:149], v[214:215], v[80:81], v[148:149] neg_hi:[1,0,0]
	v_pk_fma_f32 v[150:151], v[218:219], v[80:81], v[150:151] neg_hi:[1,0,0]
	v_pk_fma_f32 v[148:149], v[216:217], v[82:83], v[148:149] neg_hi:[1,0,0]
	v_pk_fma_f32 v[150:151], v[220:221], v[82:83], v[150:151] neg_hi:[1,0,0]
	ds_read_b128 v[164:167], v60 offset:4224
	ds_read_b128 v[194:197], v60 offset:4736
	ds_read_b128 v[198:201], v60 offset:4240
	ds_read_b128 v[202:205], v60 offset:4752
	ds_read_b128 v[206:209], v60 offset:4256
	ds_read_b128 v[210:213], v60 offset:4768
	ds_read_b128 v[214:217], v60 offset:4272
	ds_read_b128 v[218:221], v60 offset:4784
	s_waitcnt lgkmcnt(14)
	v_pk_fma_f32 v[148:149], v[186:187], v[84:85], v[148:149] neg_hi:[1,0,0]
	v_pk_fma_f32 v[150:151], v[174:175], v[84:85], v[150:151] neg_hi:[1,0,0]
	v_pk_fma_f32 v[148:149], v[188:189], v[86:87], v[148:149] neg_hi:[1,0,0]
	v_pk_fma_f32 v[150:151], v[176:177], v[86:87], v[150:151] neg_hi:[1,0,0]
	s_waitcnt lgkmcnt(12)
	v_pk_fma_f32 v[148:149], v[32:33], v[88:89], v[148:149] neg_hi:[1,0,0]
	v_pk_fma_f32 v[150:151], v[36:37], v[88:89], v[150:151] neg_hi:[1,0,0]
	v_pk_fma_f32 v[148:149], v[34:35], v[90:91], v[148:149] neg_hi:[1,0,0]
	v_pk_fma_f32 v[150:151], v[38:39], v[90:91], v[150:151] neg_hi:[1,0,0]
	s_waitcnt lgkmcnt(10)
	v_pk_fma_f32 v[148:149], v[40:41], v[92:93], v[148:149] neg_hi:[1,0,0]
	v_pk_fma_f32 v[150:151], v[44:45], v[92:93], v[150:151] neg_hi:[1,0,0]
	v_pk_fma_f32 v[148:149], v[42:43], v[94:95], v[148:149] neg_hi:[1,0,0]
	v_pk_fma_f32 v[150:151], v[46:47], v[94:95], v[150:151] neg_hi:[1,0,0]
	s_waitcnt lgkmcnt(8)
	v_pk_fma_f32 v[148:149], v[48:49], v[96:97], v[148:149] neg_hi:[1,0,0]
	v_pk_fma_f32 v[150:151], v[52:53], v[96:97], v[150:151] neg_hi:[1,0,0]
	v_pk_fma_f32 v[148:149], v[50:51], v[98:99], v[148:149] neg_hi:[1,0,0]
	v_pk_fma_f32 v[150:151], v[54:55], v[98:99], v[150:151] neg_hi:[1,0,0]
	ds_read_b128 v[186:189], v60 offset:4288
	ds_read_b128 v[174:177], v60 offset:4800
	ds_read_b128 v[32:35], v60 offset:4304
	ds_read_b128 v[36:39], v60 offset:4816
	ds_read_b128 v[40:43], v60 offset:4320
	ds_read_b128 v[44:47], v60 offset:4832
	ds_read_b128 v[48:51], v60 offset:4336
	ds_read_b128 v[52:55], v60 offset:4848
	s_waitcnt lgkmcnt(14)
	v_pk_fma_f32 v[148:149], v[164:165], v[100:101], v[148:149] neg_hi:[1,0,0]
	v_pk_fma_f32 v[150:151], v[194:195], v[100:101], v[150:151] neg_hi:[1,0,0]
	v_pk_fma_f32 v[148:149], v[166:167], v[102:103], v[148:149] neg_hi:[1,0,0]
	v_pk_fma_f32 v[150:151], v[196:197], v[102:103], v[150:151] neg_hi:[1,0,0]
	s_waitcnt lgkmcnt(12)
	v_pk_fma_f32 v[148:149], v[198:199], v[104:105], v[148:149] neg_hi:[1,0,0]
	v_pk_fma_f32 v[150:151], v[202:203], v[104:105], v[150:151] neg_hi:[1,0,0]
	v_pk_fma_f32 v[148:149], v[200:201], v[106:107], v[148:149] neg_hi:[1,0,0]
	v_pk_fma_f32 v[150:151], v[204:205], v[106:107], v[150:151] neg_hi:[1,0,0]
	s_waitcnt lgkmcnt(10)
	v_pk_fma_f32 v[148:149], v[206:207], v[108:109], v[148:149] neg_hi:[1,0,0]
	v_pk_fma_f32 v[150:151], v[210:211], v[108:109], v[150:151] neg_hi:[1,0,0]
	v_pk_fma_f32 v[148:149], v[208:209], v[110:111], v[148:149] neg_hi:[1,0,0]
	v_pk_fma_f32 v[150:151], v[212:213], v[110:111], v[150:151] neg_hi:[1,0,0]
	s_waitcnt lgkmcnt(8)
	v_pk_fma_f32 v[148:149], v[214:215], v[112:113], v[148:149] neg_hi:[1,0,0]
	v_pk_fma_f32 v[150:151], v[218:219], v[112:113], v[150:151] neg_hi:[1,0,0]
	v_pk_fma_f32 v[148:149], v[216:217], v[114:115], v[148:149] neg_hi:[1,0,0]
	v_pk_fma_f32 v[150:151], v[220:221], v[114:115], v[150:151] neg_hi:[1,0,0]
	ds_read_b128 v[164:167], v60 offset:5120
	ds_read_b128 v[194:197], v60 offset:5632
	ds_read_b128 v[198:201], v60 offset:5136
	ds_read_b128 v[202:205], v60 offset:5648
	ds_read_b128 v[206:209], v60 offset:5152
	ds_read_b128 v[210:213], v60 offset:5664
	ds_read_b128 v[214:217], v60 offset:5168
	ds_read_b128 v[218:221], v60 offset:5680
	s_waitcnt lgkmcnt(14)
	v_pk_fma_f32 v[148:149], v[186:187], v[116:117], v[148:149] neg_hi:[1,0,0]
	v_pk_fma_f32 v[150:151], v[174:175], v[116:117], v[150:151] neg_hi:[1,0,0]
	v_pk_fma_f32 v[148:149], v[188:189], v[118:119], v[148:149] neg_hi:[1,0,0]
	v_pk_fma_f32 v[150:151], v[176:177], v[118:119], v[150:151] neg_hi:[1,0,0]
	s_waitcnt lgkmcnt(12)
	v_pk_fma_f32 v[148:149], v[32:33], v[120:121], v[148:149] neg_hi:[1,0,0]
	v_pk_fma_f32 v[150:151], v[36:37], v[120:121], v[150:151] neg_hi:[1,0,0]
	v_pk_fma_f32 v[148:149], v[34:35], v[122:123], v[148:149] neg_hi:[1,0,0]
	v_pk_fma_f32 v[150:151], v[38:39], v[122:123], v[150:151] neg_hi:[1,0,0]
	s_waitcnt lgkmcnt(10)
	v_pk_fma_f32 v[148:149], v[40:41], v[124:125], v[148:149] neg_hi:[1,0,0]
	v_pk_fma_f32 v[150:151], v[44:45], v[124:125], v[150:151] neg_hi:[1,0,0]
	v_pk_fma_f32 v[148:149], v[42:43], v[126:127], v[148:149] neg_hi:[1,0,0]
	v_pk_fma_f32 v[150:151], v[46:47], v[126:127], v[150:151] neg_hi:[1,0,0]
	s_waitcnt lgkmcnt(8)
	v_pk_fma_f32 v[148:149], v[48:49], v[128:129], v[148:149] neg_hi:[1,0,0]
	v_pk_fma_f32 v[150:151], v[52:53], v[128:129], v[150:151] neg_hi:[1,0,0]
	v_pk_fma_f32 v[148:149], v[50:51], v[130:131], v[148:149] neg_hi:[1,0,0]
	v_pk_fma_f32 v[150:151], v[54:55], v[130:131], v[150:151] neg_hi:[1,0,0]
	ds_read_b128 v[186:189], v60 offset:5184
	ds_read_b128 v[174:177], v60 offset:5696
	ds_read_b128 v[32:35], v60 offset:5200
	ds_read_b128 v[36:39], v60 offset:5712
	ds_read_b128 v[40:43], v60 offset:5216
	ds_read_b128 v[44:47], v60 offset:5728
	ds_read_b128 v[48:51], v60 offset:5232
	ds_read_b128 v[52:55], v60 offset:5744
	s_waitcnt lgkmcnt(14)
	v_pk_fma_f32 v[152:153], v[164:165], v[68:69], v[152:153] neg_hi:[1,0,0]
	v_pk_fma_f32 v[154:155], v[194:195], v[68:69], v[154:155] neg_hi:[1,0,0]
	v_pk_fma_f32 v[152:153], v[166:167], v[70:71], v[152:153] neg_hi:[1,0,0]
	v_pk_fma_f32 v[154:155], v[196:197], v[70:71], v[154:155] neg_hi:[1,0,0]
	s_waitcnt lgkmcnt(12)
	v_pk_fma_f32 v[152:153], v[198:199], v[72:73], v[152:153] neg_hi:[1,0,0]
	v_pk_fma_f32 v[154:155], v[202:203], v[72:73], v[154:155] neg_hi:[1,0,0]
	v_pk_fma_f32 v[152:153], v[200:201], v[74:75], v[152:153] neg_hi:[1,0,0]
	v_pk_fma_f32 v[154:155], v[204:205], v[74:75], v[154:155] neg_hi:[1,0,0]
	s_waitcnt lgkmcnt(10)
	v_pk_fma_f32 v[152:153], v[206:207], v[76:77], v[152:153] neg_hi:[1,0,0]
	v_pk_fma_f32 v[154:155], v[210:211], v[76:77], v[154:155] neg_hi:[1,0,0]
	v_pk_fma_f32 v[152:153], v[208:209], v[78:79], v[152:153] neg_hi:[1,0,0]
	v_pk_fma_f32 v[154:155], v[212:213], v[78:79], v[154:155] neg_hi:[1,0,0]
	s_waitcnt lgkmcnt(8)
	v_pk_fma_f32 v[152:153], v[214:215], v[80:81], v[152:153] neg_hi:[1,0,0]
	v_pk_fma_f32 v[154:155], v[218:219], v[80:81], v[154:155] neg_hi:[1,0,0]
	v_pk_fma_f32 v[152:153], v[216:217], v[82:83], v[152:153] neg_hi:[1,0,0]
	v_pk_fma_f32 v[154:155], v[220:221], v[82:83], v[154:155] neg_hi:[1,0,0]
	ds_read_b128 v[164:167], v60 offset:5248
	ds_read_b128 v[194:197], v60 offset:5760
	ds_read_b128 v[198:201], v60 offset:5264
	ds_read_b128 v[202:205], v60 offset:5776
	ds_read_b128 v[206:209], v60 offset:5280
	ds_read_b128 v[210:213], v60 offset:5792
	ds_read_b128 v[214:217], v60 offset:5296
	ds_read_b128 v[218:221], v60 offset:5808
	s_waitcnt lgkmcnt(14)
	v_pk_fma_f32 v[152:153], v[186:187], v[84:85], v[152:153] neg_hi:[1,0,0]
	v_pk_fma_f32 v[154:155], v[174:175], v[84:85], v[154:155] neg_hi:[1,0,0]
	v_pk_fma_f32 v[152:153], v[188:189], v[86:87], v[152:153] neg_hi:[1,0,0]
	v_pk_fma_f32 v[154:155], v[176:177], v[86:87], v[154:155] neg_hi:[1,0,0]
	s_waitcnt lgkmcnt(12)
	v_pk_fma_f32 v[152:153], v[32:33], v[88:89], v[152:153] neg_hi:[1,0,0]
	v_pk_fma_f32 v[154:155], v[36:37], v[88:89], v[154:155] neg_hi:[1,0,0]
	v_pk_fma_f32 v[152:153], v[34:35], v[90:91], v[152:153] neg_hi:[1,0,0]
	v_pk_fma_f32 v[154:155], v[38:39], v[90:91], v[154:155] neg_hi:[1,0,0]
	s_waitcnt lgkmcnt(10)
	v_pk_fma_f32 v[152:153], v[40:41], v[92:93], v[152:153] neg_hi:[1,0,0]
	v_pk_fma_f32 v[154:155], v[44:45], v[92:93], v[154:155] neg_hi:[1,0,0]
	v_pk_fma_f32 v[152:153], v[42:43], v[94:95], v[152:153] neg_hi:[1,0,0]
	v_pk_fma_f32 v[154:155], v[46:47], v[94:95], v[154:155] neg_hi:[1,0,0]
	s_waitcnt lgkmcnt(8)
	v_pk_fma_f32 v[152:153], v[48:49], v[96:97], v[152:153] neg_hi:[1,0,0]
	v_pk_fma_f32 v[154:155], v[52:53], v[96:97], v[154:155] neg_hi:[1,0,0]
	v_pk_fma_f32 v[152:153], v[50:51], v[98:99], v[152:153] neg_hi:[1,0,0]
	v_pk_fma_f32 v[154:155], v[54:55], v[98:99], v[154:155] neg_hi:[1,0,0]
	ds_read_b128 v[186:189], v60 offset:5312
	ds_read_b128 v[174:177], v60 offset:5824
	ds_read_b128 v[32:35], v60 offset:5328
	ds_read_b128 v[36:39], v60 offset:5840
	ds_read_b128 v[40:43], v60 offset:5344
	ds_read_b128 v[44:47], v60 offset:5856
	ds_read_b128 v[48:51], v60 offset:5360
	ds_read_b128 v[52:55], v60 offset:5872
	s_waitcnt lgkmcnt(14)
	v_pk_fma_f32 v[152:153], v[164:165], v[100:101], v[152:153] neg_hi:[1,0,0]
	v_pk_fma_f32 v[154:155], v[194:195], v[100:101], v[154:155] neg_hi:[1,0,0]
	v_pk_fma_f32 v[152:153], v[166:167], v[102:103], v[152:153] neg_hi:[1,0,0]
	v_pk_fma_f32 v[154:155], v[196:197], v[102:103], v[154:155] neg_hi:[1,0,0]
	s_waitcnt lgkmcnt(12)
	v_pk_fma_f32 v[152:153], v[198:199], v[104:105], v[152:153] neg_hi:[1,0,0]
	v_pk_fma_f32 v[154:155], v[202:203], v[104:105], v[154:155] neg_hi:[1,0,0]
	v_pk_fma_f32 v[152:153], v[200:201], v[106:107], v[152:153] neg_hi:[1,0,0]
	v_pk_fma_f32 v[154:155], v[204:205], v[106:107], v[154:155] neg_hi:[1,0,0]
	s_waitcnt lgkmcnt(10)
	v_pk_fma_f32 v[152:153], v[206:207], v[108:109], v[152:153] neg_hi:[1,0,0]
	v_pk_fma_f32 v[154:155], v[210:211], v[108:109], v[154:155] neg_hi:[1,0,0]
	v_pk_fma_f32 v[152:153], v[208:209], v[110:111], v[152:153] neg_hi:[1,0,0]
	v_pk_fma_f32 v[154:155], v[212:213], v[110:111], v[154:155] neg_hi:[1,0,0]
	s_waitcnt lgkmcnt(8)
	v_pk_fma_f32 v[152:153], v[214:215], v[112:113], v[152:153] neg_hi:[1,0,0]
	v_pk_fma_f32 v[154:155], v[218:219], v[112:113], v[154:155] neg_hi:[1,0,0]
	v_pk_fma_f32 v[152:153], v[216:217], v[114:115], v[152:153] neg_hi:[1,0,0]
	v_pk_fma_f32 v[154:155], v[220:221], v[114:115], v[154:155] neg_hi:[1,0,0]
	ds_read_b128 v[164:167], v60 offset:6144
	ds_read_b128 v[194:197], v60 offset:6656
	ds_read_b128 v[198:201], v60 offset:6160
	ds_read_b128 v[202:205], v60 offset:6672
	ds_read_b128 v[206:209], v60 offset:6176
	ds_read_b128 v[210:213], v60 offset:6688
	ds_read_b128 v[214:217], v60 offset:6192
	ds_read_b128 v[218:221], v60 offset:6704
	s_waitcnt lgkmcnt(14)
	v_pk_fma_f32 v[152:153], v[186:187], v[116:117], v[152:153] neg_hi:[1,0,0]
	v_pk_fma_f32 v[154:155], v[174:175], v[116:117], v[154:155] neg_hi:[1,0,0]
	v_pk_fma_f32 v[152:153], v[188:189], v[118:119], v[152:153] neg_hi:[1,0,0]
	v_pk_fma_f32 v[154:155], v[176:177], v[118:119], v[154:155] neg_hi:[1,0,0]
	s_waitcnt lgkmcnt(12)
	v_pk_fma_f32 v[152:153], v[32:33], v[120:121], v[152:153] neg_hi:[1,0,0]
	v_pk_fma_f32 v[154:155], v[36:37], v[120:121], v[154:155] neg_hi:[1,0,0]
	v_pk_fma_f32 v[152:153], v[34:35], v[122:123], v[152:153] neg_hi:[1,0,0]
	v_pk_fma_f32 v[154:155], v[38:39], v[122:123], v[154:155] neg_hi:[1,0,0]
	s_waitcnt lgkmcnt(10)
	v_pk_fma_f32 v[152:153], v[40:41], v[124:125], v[152:153] neg_hi:[1,0,0]
	v_pk_fma_f32 v[154:155], v[44:45], v[124:125], v[154:155] neg_hi:[1,0,0]
	v_pk_fma_f32 v[152:153], v[42:43], v[126:127], v[152:153] neg_hi:[1,0,0]
	v_pk_fma_f32 v[154:155], v[46:47], v[126:127], v[154:155] neg_hi:[1,0,0]
	s_waitcnt lgkmcnt(8)
	v_pk_fma_f32 v[152:153], v[48:49], v[128:129], v[152:153] neg_hi:[1,0,0]
	v_pk_fma_f32 v[154:155], v[52:53], v[128:129], v[154:155] neg_hi:[1,0,0]
	v_pk_fma_f32 v[152:153], v[50:51], v[130:131], v[152:153] neg_hi:[1,0,0]
	v_pk_fma_f32 v[154:155], v[54:55], v[130:131], v[154:155] neg_hi:[1,0,0]
	ds_read_b128 v[186:189], v60 offset:6208
	ds_read_b128 v[174:177], v60 offset:6720
	ds_read_b128 v[32:35], v60 offset:6224
	ds_read_b128 v[36:39], v60 offset:6736
	ds_read_b128 v[40:43], v60 offset:6240
	ds_read_b128 v[44:47], v60 offset:6752
	ds_read_b128 v[48:51], v60 offset:6256
	ds_read_b128 v[52:55], v60 offset:6768
	s_waitcnt lgkmcnt(14)
	v_pk_fma_f32 v[156:157], v[164:165], v[68:69], v[156:157] neg_hi:[1,0,0]
	v_pk_fma_f32 v[158:159], v[194:195], v[68:69], v[158:159] neg_hi:[1,0,0]
	v_pk_fma_f32 v[156:157], v[166:167], v[70:71], v[156:157] neg_hi:[1,0,0]
	v_pk_fma_f32 v[158:159], v[196:197], v[70:71], v[158:159] neg_hi:[1,0,0]
	s_waitcnt lgkmcnt(12)
	v_pk_fma_f32 v[156:157], v[198:199], v[72:73], v[156:157] neg_hi:[1,0,0]
	v_pk_fma_f32 v[158:159], v[202:203], v[72:73], v[158:159] neg_hi:[1,0,0]
	v_pk_fma_f32 v[156:157], v[200:201], v[74:75], v[156:157] neg_hi:[1,0,0]
	v_pk_fma_f32 v[158:159], v[204:205], v[74:75], v[158:159] neg_hi:[1,0,0]
	s_waitcnt lgkmcnt(10)
	v_pk_fma_f32 v[156:157], v[206:207], v[76:77], v[156:157] neg_hi:[1,0,0]
	v_pk_fma_f32 v[158:159], v[210:211], v[76:77], v[158:159] neg_hi:[1,0,0]
	v_pk_fma_f32 v[156:157], v[208:209], v[78:79], v[156:157] neg_hi:[1,0,0]
	v_pk_fma_f32 v[158:159], v[212:213], v[78:79], v[158:159] neg_hi:[1,0,0]
	s_waitcnt lgkmcnt(8)
	v_pk_fma_f32 v[156:157], v[214:215], v[80:81], v[156:157] neg_hi:[1,0,0]
	v_pk_fma_f32 v[158:159], v[218:219], v[80:81], v[158:159] neg_hi:[1,0,0]
	v_pk_fma_f32 v[156:157], v[216:217], v[82:83], v[156:157] neg_hi:[1,0,0]
	v_pk_fma_f32 v[158:159], v[220:221], v[82:83], v[158:159] neg_hi:[1,0,0]
	ds_read_b128 v[164:167], v60 offset:6272
	ds_read_b128 v[194:197], v60 offset:6784
	ds_read_b128 v[198:201], v60 offset:6288
	ds_read_b128 v[202:205], v60 offset:6800
	ds_read_b128 v[206:209], v60 offset:6304
	ds_read_b128 v[210:213], v60 offset:6816
	ds_read_b128 v[214:217], v60 offset:6320
	ds_read_b128 v[218:221], v60 offset:6832
	s_waitcnt lgkmcnt(14)
	v_pk_fma_f32 v[156:157], v[186:187], v[84:85], v[156:157] neg_hi:[1,0,0]
	v_pk_fma_f32 v[158:159], v[174:175], v[84:85], v[158:159] neg_hi:[1,0,0]
	v_pk_fma_f32 v[156:157], v[188:189], v[86:87], v[156:157] neg_hi:[1,0,0]
	v_pk_fma_f32 v[158:159], v[176:177], v[86:87], v[158:159] neg_hi:[1,0,0]
	s_waitcnt lgkmcnt(12)
	v_pk_fma_f32 v[156:157], v[32:33], v[88:89], v[156:157] neg_hi:[1,0,0]
	v_pk_fma_f32 v[158:159], v[36:37], v[88:89], v[158:159] neg_hi:[1,0,0]
	v_pk_fma_f32 v[156:157], v[34:35], v[90:91], v[156:157] neg_hi:[1,0,0]
	v_pk_fma_f32 v[158:159], v[38:39], v[90:91], v[158:159] neg_hi:[1,0,0]
	s_waitcnt lgkmcnt(10)
	v_pk_fma_f32 v[156:157], v[40:41], v[92:93], v[156:157] neg_hi:[1,0,0]
	v_pk_fma_f32 v[158:159], v[44:45], v[92:93], v[158:159] neg_hi:[1,0,0]
	v_pk_fma_f32 v[156:157], v[42:43], v[94:95], v[156:157] neg_hi:[1,0,0]
	v_pk_fma_f32 v[158:159], v[46:47], v[94:95], v[158:159] neg_hi:[1,0,0]
	s_waitcnt lgkmcnt(8)
	v_pk_fma_f32 v[156:157], v[48:49], v[96:97], v[156:157] neg_hi:[1,0,0]
	v_pk_fma_f32 v[158:159], v[52:53], v[96:97], v[158:159] neg_hi:[1,0,0]
	v_pk_fma_f32 v[156:157], v[50:51], v[98:99], v[156:157] neg_hi:[1,0,0]
	v_pk_fma_f32 v[158:159], v[54:55], v[98:99], v[158:159] neg_hi:[1,0,0]
	ds_read_b128 v[186:189], v60 offset:6336
	ds_read_b128 v[174:177], v60 offset:6848
	ds_read_b128 v[32:35], v60 offset:6352
	ds_read_b128 v[36:39], v60 offset:6864
	ds_read_b128 v[40:43], v60 offset:6368
	ds_read_b128 v[44:47], v60 offset:6880
	ds_read_b128 v[48:51], v60 offset:6384
	ds_read_b128 v[52:55], v60 offset:6896
	s_waitcnt lgkmcnt(14)
	v_pk_fma_f32 v[156:157], v[164:165], v[100:101], v[156:157] neg_hi:[1,0,0]
	v_pk_fma_f32 v[158:159], v[194:195], v[100:101], v[158:159] neg_hi:[1,0,0]
	v_pk_fma_f32 v[156:157], v[166:167], v[102:103], v[156:157] neg_hi:[1,0,0]
	v_pk_fma_f32 v[158:159], v[196:197], v[102:103], v[158:159] neg_hi:[1,0,0]
	s_waitcnt lgkmcnt(12)
	v_pk_fma_f32 v[156:157], v[198:199], v[104:105], v[156:157] neg_hi:[1,0,0]
	v_pk_fma_f32 v[158:159], v[202:203], v[104:105], v[158:159] neg_hi:[1,0,0]
	v_pk_fma_f32 v[156:157], v[200:201], v[106:107], v[156:157] neg_hi:[1,0,0]
	v_pk_fma_f32 v[158:159], v[204:205], v[106:107], v[158:159] neg_hi:[1,0,0]
	s_waitcnt lgkmcnt(10)
	v_pk_fma_f32 v[156:157], v[206:207], v[108:109], v[156:157] neg_hi:[1,0,0]
	v_pk_fma_f32 v[158:159], v[210:211], v[108:109], v[158:159] neg_hi:[1,0,0]
	v_pk_fma_f32 v[156:157], v[208:209], v[110:111], v[156:157] neg_hi:[1,0,0]
	v_pk_fma_f32 v[158:159], v[212:213], v[110:111], v[158:159] neg_hi:[1,0,0]
	s_waitcnt lgkmcnt(8)
	v_pk_fma_f32 v[156:157], v[214:215], v[112:113], v[156:157] neg_hi:[1,0,0]
	v_pk_fma_f32 v[158:159], v[218:219], v[112:113], v[158:159] neg_hi:[1,0,0]
	v_pk_fma_f32 v[156:157], v[216:217], v[114:115], v[156:157] neg_hi:[1,0,0]
	v_pk_fma_f32 v[158:159], v[220:221], v[114:115], v[158:159] neg_hi:[1,0,0]
	ds_read_b128 v[164:167], v60 offset:7168
	ds_read_b128 v[194:197], v60 offset:7680
	ds_read_b128 v[198:201], v60 offset:7184
	ds_read_b128 v[202:205], v60 offset:7696
	ds_read_b128 v[206:209], v60 offset:7200
	ds_read_b128 v[210:213], v60 offset:7712
	ds_read_b128 v[214:217], v60 offset:7216
	ds_read_b128 v[218:221], v60 offset:7728
	s_waitcnt lgkmcnt(14)
	v_pk_fma_f32 v[156:157], v[186:187], v[116:117], v[156:157] neg_hi:[1,0,0]
	v_pk_fma_f32 v[158:159], v[174:175], v[116:117], v[158:159] neg_hi:[1,0,0]
	v_pk_fma_f32 v[156:157], v[188:189], v[118:119], v[156:157] neg_hi:[1,0,0]
	v_pk_fma_f32 v[158:159], v[176:177], v[118:119], v[158:159] neg_hi:[1,0,0]
	s_waitcnt lgkmcnt(12)
	v_pk_fma_f32 v[156:157], v[32:33], v[120:121], v[156:157] neg_hi:[1,0,0]
	v_pk_fma_f32 v[158:159], v[36:37], v[120:121], v[158:159] neg_hi:[1,0,0]
	v_pk_fma_f32 v[156:157], v[34:35], v[122:123], v[156:157] neg_hi:[1,0,0]
	v_pk_fma_f32 v[158:159], v[38:39], v[122:123], v[158:159] neg_hi:[1,0,0]
	s_waitcnt lgkmcnt(10)
	v_pk_fma_f32 v[156:157], v[40:41], v[124:125], v[156:157] neg_hi:[1,0,0]
	v_pk_fma_f32 v[158:159], v[44:45], v[124:125], v[158:159] neg_hi:[1,0,0]
	v_pk_fma_f32 v[156:157], v[42:43], v[126:127], v[156:157] neg_hi:[1,0,0]
	v_pk_fma_f32 v[158:159], v[46:47], v[126:127], v[158:159] neg_hi:[1,0,0]
	s_waitcnt lgkmcnt(8)
	v_pk_fma_f32 v[156:157], v[48:49], v[128:129], v[156:157] neg_hi:[1,0,0]
	v_pk_fma_f32 v[158:159], v[52:53], v[128:129], v[158:159] neg_hi:[1,0,0]
	v_pk_fma_f32 v[156:157], v[50:51], v[130:131], v[156:157] neg_hi:[1,0,0]
	v_pk_fma_f32 v[158:159], v[54:55], v[130:131], v[158:159] neg_hi:[1,0,0]
	ds_read_b128 v[186:189], v60 offset:7232
	ds_read_b128 v[174:177], v60 offset:7744
	ds_read_b128 v[32:35], v60 offset:7248
	ds_read_b128 v[36:39], v60 offset:7760
	ds_read_b128 v[40:43], v60 offset:7264
	ds_read_b128 v[44:47], v60 offset:7776
	ds_read_b128 v[48:51], v60 offset:7280
	ds_read_b128 v[52:55], v60 offset:7792
	s_waitcnt lgkmcnt(14)
	v_pk_fma_f32 v[160:161], v[164:165], v[68:69], v[160:161] neg_hi:[1,0,0]
	v_pk_fma_f32 v[162:163], v[194:195], v[68:69], v[162:163] neg_hi:[1,0,0]
	v_pk_fma_f32 v[160:161], v[166:167], v[70:71], v[160:161] neg_hi:[1,0,0]
	v_pk_fma_f32 v[162:163], v[196:197], v[70:71], v[162:163] neg_hi:[1,0,0]
	s_waitcnt lgkmcnt(12)
	v_pk_fma_f32 v[160:161], v[198:199], v[72:73], v[160:161] neg_hi:[1,0,0]
	v_pk_fma_f32 v[162:163], v[202:203], v[72:73], v[162:163] neg_hi:[1,0,0]
	v_pk_fma_f32 v[160:161], v[200:201], v[74:75], v[160:161] neg_hi:[1,0,0]
	v_pk_fma_f32 v[162:163], v[204:205], v[74:75], v[162:163] neg_hi:[1,0,0]
	s_waitcnt lgkmcnt(10)
	v_pk_fma_f32 v[160:161], v[206:207], v[76:77], v[160:161] neg_hi:[1,0,0]
	v_pk_fma_f32 v[162:163], v[210:211], v[76:77], v[162:163] neg_hi:[1,0,0]
	v_pk_fma_f32 v[160:161], v[208:209], v[78:79], v[160:161] neg_hi:[1,0,0]
	v_pk_fma_f32 v[162:163], v[212:213], v[78:79], v[162:163] neg_hi:[1,0,0]
	s_waitcnt lgkmcnt(8)
	v_pk_fma_f32 v[160:161], v[214:215], v[80:81], v[160:161] neg_hi:[1,0,0]
	v_pk_fma_f32 v[162:163], v[218:219], v[80:81], v[162:163] neg_hi:[1,0,0]
	v_pk_fma_f32 v[160:161], v[216:217], v[82:83], v[160:161] neg_hi:[1,0,0]
	v_pk_fma_f32 v[162:163], v[220:221], v[82:83], v[162:163] neg_hi:[1,0,0]
	ds_read_b128 v[164:167], v60 offset:7296
	ds_read_b128 v[194:197], v60 offset:7808
	ds_read_b128 v[198:201], v60 offset:7312
	ds_read_b128 v[202:205], v60 offset:7824
	ds_read_b128 v[206:209], v60 offset:7328
	ds_read_b128 v[210:213], v60 offset:7840
	ds_read_b128 v[214:217], v60 offset:7344
	ds_read_b128 v[218:221], v60 offset:7856
	s_waitcnt lgkmcnt(14)
	v_pk_fma_f32 v[160:161], v[186:187], v[84:85], v[160:161] neg_hi:[1,0,0]
	v_pk_fma_f32 v[162:163], v[174:175], v[84:85], v[162:163] neg_hi:[1,0,0]
	v_pk_fma_f32 v[160:161], v[188:189], v[86:87], v[160:161] neg_hi:[1,0,0]
	v_pk_fma_f32 v[162:163], v[176:177], v[86:87], v[162:163] neg_hi:[1,0,0]
	s_waitcnt lgkmcnt(12)
	v_pk_fma_f32 v[160:161], v[32:33], v[88:89], v[160:161] neg_hi:[1,0,0]
	v_pk_fma_f32 v[162:163], v[36:37], v[88:89], v[162:163] neg_hi:[1,0,0]
	v_pk_fma_f32 v[160:161], v[34:35], v[90:91], v[160:161] neg_hi:[1,0,0]
	v_pk_fma_f32 v[162:163], v[38:39], v[90:91], v[162:163] neg_hi:[1,0,0]
	s_waitcnt lgkmcnt(10)
	v_pk_fma_f32 v[160:161], v[40:41], v[92:93], v[160:161] neg_hi:[1,0,0]
	v_pk_fma_f32 v[162:163], v[44:45], v[92:93], v[162:163] neg_hi:[1,0,0]
	v_pk_fma_f32 v[160:161], v[42:43], v[94:95], v[160:161] neg_hi:[1,0,0]
	v_pk_fma_f32 v[162:163], v[46:47], v[94:95], v[162:163] neg_hi:[1,0,0]
	s_waitcnt lgkmcnt(8)
	v_pk_fma_f32 v[160:161], v[48:49], v[96:97], v[160:161] neg_hi:[1,0,0]
	v_pk_fma_f32 v[162:163], v[52:53], v[96:97], v[162:163] neg_hi:[1,0,0]
	v_pk_fma_f32 v[160:161], v[50:51], v[98:99], v[160:161] neg_hi:[1,0,0]
	v_pk_fma_f32 v[162:163], v[54:55], v[98:99], v[162:163] neg_hi:[1,0,0]
	ds_read_b128 v[186:189], v60 offset:7360
	ds_read_b128 v[174:177], v60 offset:7872
	ds_read_b128 v[32:35], v60 offset:7376
	ds_read_b128 v[36:39], v60 offset:7888
	ds_read_b128 v[40:43], v60 offset:7392
	ds_read_b128 v[44:47], v60 offset:7904
	ds_read_b128 v[48:51], v60 offset:7408
	ds_read_b128 v[52:55], v60 offset:7920
	s_waitcnt lgkmcnt(14)
	v_pk_fma_f32 v[160:161], v[164:165], v[100:101], v[160:161] neg_hi:[1,0,0]
	v_pk_fma_f32 v[162:163], v[194:195], v[100:101], v[162:163] neg_hi:[1,0,0]
	v_pk_fma_f32 v[160:161], v[166:167], v[102:103], v[160:161] neg_hi:[1,0,0]
	v_pk_fma_f32 v[162:163], v[196:197], v[102:103], v[162:163] neg_hi:[1,0,0]
	s_waitcnt lgkmcnt(12)
	v_pk_fma_f32 v[160:161], v[198:199], v[104:105], v[160:161] neg_hi:[1,0,0]
	v_pk_fma_f32 v[162:163], v[202:203], v[104:105], v[162:163] neg_hi:[1,0,0]
	v_pk_fma_f32 v[160:161], v[200:201], v[106:107], v[160:161] neg_hi:[1,0,0]
	v_pk_fma_f32 v[162:163], v[204:205], v[106:107], v[162:163] neg_hi:[1,0,0]
	s_waitcnt lgkmcnt(10)
	v_pk_fma_f32 v[160:161], v[206:207], v[108:109], v[160:161] neg_hi:[1,0,0]
	v_pk_fma_f32 v[162:163], v[210:211], v[108:109], v[162:163] neg_hi:[1,0,0]
	v_pk_fma_f32 v[160:161], v[208:209], v[110:111], v[160:161] neg_hi:[1,0,0]
	v_pk_fma_f32 v[162:163], v[212:213], v[110:111], v[162:163] neg_hi:[1,0,0]
	s_waitcnt lgkmcnt(8)
	v_pk_fma_f32 v[160:161], v[214:215], v[112:113], v[160:161] neg_hi:[1,0,0]
	v_pk_fma_f32 v[162:163], v[218:219], v[112:113], v[162:163] neg_hi:[1,0,0]
	v_pk_fma_f32 v[160:161], v[216:217], v[114:115], v[160:161] neg_hi:[1,0,0]
	v_pk_fma_f32 v[162:163], v[220:221], v[114:115], v[162:163] neg_hi:[1,0,0]
	s_waitcnt lgkmcnt(6)
	v_pk_fma_f32 v[160:161], v[186:187], v[116:117], v[160:161] neg_hi:[1,0,0]
	v_pk_fma_f32 v[162:163], v[174:175], v[116:117], v[162:163] neg_hi:[1,0,0]
	v_pk_fma_f32 v[160:161], v[188:189], v[118:119], v[160:161] neg_hi:[1,0,0]
	v_pk_fma_f32 v[162:163], v[176:177], v[118:119], v[162:163] neg_hi:[1,0,0]
	s_waitcnt lgkmcnt(4)
	v_pk_fma_f32 v[160:161], v[32:33], v[120:121], v[160:161] neg_hi:[1,0,0]
	v_pk_fma_f32 v[162:163], v[36:37], v[120:121], v[162:163] neg_hi:[1,0,0]
	v_pk_fma_f32 v[160:161], v[34:35], v[122:123], v[160:161] neg_hi:[1,0,0]
	v_pk_fma_f32 v[162:163], v[38:39], v[122:123], v[162:163] neg_hi:[1,0,0]
	s_waitcnt lgkmcnt(2)
	v_pk_fma_f32 v[160:161], v[40:41], v[124:125], v[160:161] neg_hi:[1,0,0]
	v_pk_fma_f32 v[162:163], v[44:45], v[124:125], v[162:163] neg_hi:[1,0,0]
	v_pk_fma_f32 v[160:161], v[42:43], v[126:127], v[160:161] neg_hi:[1,0,0]
	v_pk_fma_f32 v[162:163], v[46:47], v[126:127], v[162:163] neg_hi:[1,0,0]
	s_waitcnt lgkmcnt(0)
	v_pk_fma_f32 v[160:161], v[48:49], v[128:129], v[160:161] neg_hi:[1,0,0]
	v_pk_fma_f32 v[162:163], v[52:53], v[128:129], v[162:163] neg_hi:[1,0,0]
	v_pk_fma_f32 v[160:161], v[50:51], v[130:131], v[160:161] neg_hi:[1,0,0]
	v_pk_fma_f32 v[162:163], v[54:55], v[130:131], v[162:163] neg_hi:[1,0,0]
.Ltmz_skip:
	s_or_b64 exec, exec, s[62:63]
	s_add_i32 s2, s2, 1
	s_cmp_lt_u32 s2, 4
	s_cbranch_scc1 .Ltmz_it
	s_movk_i32 s56, 0x1000
	s_mov_b32 s57, 0
	v_lshl_add_u64 v[62:63], v[10:11], 0, s[56:57]
	v_lshl_add_u64 v[64:65], v[62:63], 0, s[56:57]
	v_lshl_add_u64 v[66:67], v[64:65], 0, s[56:57]
	s_waitcnt vmcnt(0)
	v_cndmask_b32_e32 v26, 0, v26, vcc
	v_add_f32_e32 v132, v132, v133
	v_cmp_eq_u32_e64 s[0:1], 0, v4
	v_cndmask_b32_e64 v133, 0, v26, s[0:1]
	v_add_f32_e32 v132, v132, v133
	v_cvt_pk_bf16_f32 v132, v132, v132
	global_store_short v[10:11], v132, off
	v_add_f32_e32 v134, v134, v135
	v_cmp_eq_u32_e64 s[0:1], 1, v4
	v_cndmask_b32_e64 v135, 0, v26, s[0:1]
	v_add_f32_e32 v134, v134, v135
	v_cvt_pk_bf16_f32 v134, v134, v134
	global_store_short v[10:11], v134, off offset:1024
	v_add_f32_e32 v136, v136, v137
	v_cmp_eq_u32_e64 s[0:1], 2, v4
	v_cndmask_b32_e64 v137, 0, v26, s[0:1]
	v_add_f32_e32 v136, v136, v137
	v_cvt_pk_bf16_f32 v136, v136, v136
	global_store_short v[10:11], v136, off offset:2048
	v_add_f32_e32 v138, v138, v139
	v_cmp_eq_u32_e64 s[0:1], 3, v4
	v_cndmask_b32_e64 v139, 0, v26, s[0:1]
	v_add_f32_e32 v138, v138, v139
	v_cvt_pk_bf16_f32 v138, v138, v138
	global_store_short v[10:11], v138, off offset:3072
	v_add_f32_e32 v140, v140, v141
	v_cmp_eq_u32_e64 s[0:1], 4, v4
	v_cndmask_b32_e64 v141, 0, v26, s[0:1]
	v_add_f32_e32 v140, v140, v141
	v_cvt_pk_bf16_f32 v140, v140, v140
	global_store_short v[62:63], v140, off
	v_add_f32_e32 v142, v142, v143
	v_cmp_eq_u32_e64 s[0:1], 5, v4
	v_cndmask_b32_e64 v143, 0, v26, s[0:1]
	v_add_f32_e32 v142, v142, v143
	v_cvt_pk_bf16_f32 v142, v142, v142
	global_store_short v[62:63], v142, off offset:1024
	v_add_f32_e32 v144, v144, v145
	v_cmp_eq_u32_e64 s[0:1], 6, v4
	v_cndmask_b32_e64 v145, 0, v26, s[0:1]
	v_add_f32_e32 v144, v144, v145
	v_cvt_pk_bf16_f32 v144, v144, v144
	global_store_short v[62:63], v144, off offset:2048
	v_add_f32_e32 v146, v146, v147
	v_cmp_eq_u32_e64 s[0:1], 7, v4
	v_cndmask_b32_e64 v147, 0, v26, s[0:1]
	v_add_f32_e32 v146, v146, v147
	v_cvt_pk_bf16_f32 v146, v146, v146
	global_store_short v[62:63], v146, off offset:3072
	v_add_f32_e32 v148, v148, v149
	v_cmp_eq_u32_e64 s[0:1], 8, v4
	v_cndmask_b32_e64 v149, 0, v26, s[0:1]
	v_add_f32_e32 v148, v148, v149
	v_cvt_pk_bf16_f32 v148, v148, v148
	global_store_short v[64:65], v148, off
	v_add_f32_e32 v150, v150, v151
	v_cmp_eq_u32_e64 s[0:1], 9, v4
	v_cndmask_b32_e64 v151, 0, v26, s[0:1]
	v_add_f32_e32 v150, v150, v151
	v_cvt_pk_bf16_f32 v150, v150, v150
	global_store_short v[64:65], v150, off offset:1024
	v_add_f32_e32 v152, v152, v153
	v_cmp_eq_u32_e64 s[0:1], 10, v4
	v_cndmask_b32_e64 v153, 0, v26, s[0:1]
	v_add_f32_e32 v152, v152, v153
	v_cvt_pk_bf16_f32 v152, v152, v152
	global_store_short v[64:65], v152, off offset:2048
	v_add_f32_e32 v154, v154, v155
	v_cmp_eq_u32_e64 s[0:1], 11, v4
	v_cndmask_b32_e64 v155, 0, v26, s[0:1]
	v_add_f32_e32 v154, v154, v155
	v_cvt_pk_bf16_f32 v154, v154, v154
	global_store_short v[64:65], v154, off offset:3072
	v_add_f32_e32 v156, v156, v157
	v_cmp_eq_u32_e64 s[0:1], 12, v4
	v_cndmask_b32_e64 v157, 0, v26, s[0:1]
	v_add_f32_e32 v156, v156, v157
	v_cvt_pk_bf16_f32 v156, v156, v156
	global_store_short v[66:67], v156, off
	v_add_f32_e32 v158, v158, v159
	v_cmp_eq_u32_e64 s[0:1], 13, v4
	v_cndmask_b32_e64 v159, 0, v26, s[0:1]
	v_add_f32_e32 v158, v158, v159
	v_cvt_pk_bf16_f32 v158, v158, v158
	global_store_short v[66:67], v158, off offset:1024
	v_add_f32_e32 v160, v160, v161
	v_cmp_eq_u32_e64 s[0:1], 14, v4
	v_cndmask_b32_e64 v161, 0, v26, s[0:1]
	v_add_f32_e32 v160, v160, v161
	v_cvt_pk_bf16_f32 v160, v160, v160
	global_store_short v[66:67], v160, off offset:2048
	v_add_f32_e32 v162, v162, v163
	v_cmp_eq_u32_e64 s[0:1], 15, v4
	v_cndmask_b32_e64 v163, 0, v26, s[0:1]
	v_add_f32_e32 v162, v162, v163
	v_cvt_pk_bf16_f32 v162, v162, v162
	global_store_short v[66:67], v162, off offset:3072
	s_branch .LBB0_1723
